# v88 + noprio: per-segment s_setprio toggling removed from all GEMM K loops
# speedup vs baseline: 1.0034x; 1.0006x over previous
; #define PG8_STAGE(bufoff, gbase, voff) do { _Pragma("unroll") for (int _i = 0; _i < 2; ++_i) \
;         __builtin_amdgcn_global_load_lds((const unsigned*)((const char*)(gbase) + (voff)[_i]), (PG8_LAS unsigned*)(lds + (bufoff) + ldsw + _i * 8192), 16, 0, 0); } while (0)
; #define PG8_LDA(dst, b, h) do { _Pragma("unroll") for (int m = 0; m < 4; ++m) _Pragma("unroll") for (int k = 0; k < 2; ++k) dst[m][k] = *(const PG8_LAS bf16x8*)(lds + PG8_SA(b, h) + aoff + m * 2048 + k * 1024); } while (0)
; #define PG8_LDB(dst, b, h) do { _Pragma("unroll") for (int n = 0; n < 2; ++n) _Pragma("unroll") for (int k = 0; k < 2; ++k) dst[n][k] = *(const PG8_LAS bf16x8*)(lds + PG8_SB(b, h) + boff + n * 2048 + k * 1024); } while (0)
; #define PG8_MMA(ai, bj, At, Bt) do { __builtin_amdgcn_s_setprio(1); _Pragma("unroll") for (int m = 0; m < 4; ++m) _Pragma("unroll") for (int n = 0; n < 2; ++n) _Pragma("unroll") for (int k = 0; k < 2; ++k) \
;         acc[ai][bj][m][n] = mma16<F16>(Bt[n][k], At[m][k], acc[ai][bj][m][n]); __builtin_amdgcn_s_setprio(0); } while (0)
; #define PG8_WAIT_V(n) asm volatile("s_waitcnt vmcnt(" #n ")" ::: "memory")
; #define PG8_WAIT_L(n) asm volatile("s_waitcnt lgkmcnt(" #n ")" ::: "memory")
; #define PG8_BAR __builtin_amdgcn_s_barrier()
; #define PG8_SCHED __builtin_amdgcn_sched_barrier(0)
; template <class Epi, class Sched, bool ALIGN_EPI = false, bool SP2 = false, bool F16 = false>
; __device__ __forceinline__ void gemm_phase(PG8_LAS unsigned char* lds, const Gemm g, const Sched& S, const Epi& E) {
;     ...
;             PG8_LDB(B0, 0, 0); PG8_LDB(B1, 0, 1); PG8_SCHED; PG8_LDA(At, 0, 0); PG8_STAGE(PG8_SA(1, 1), a1 + hstep, voffA);
;             PG8_WAIT_V(8); PG8_WAIT_L(0); PG8_BAR; PG8_MMA(0, 0, At, B0); PG8_MMA(0, 1, At, B1); PG8_BAR; PG8_SCHED;
;             PG8_LDA(At, 0, 1); PG8_STAGE(PG8_SB(0, 0), b2, voffB); PG8_STAGE(PG8_SB(0, 1), b2 + hstep, voffB); PG8_STAGE(PG8_SA(0, 0), a2, voffA);
;             PG8_WAIT_V(8); PG8_WAIT_L(0); PG8_BAR; PG8_MMA(1, 0, At, B0); PG8_MMA(1, 1, At, B1); PG8_BAR; PG8_SCHED;
.LBB0_178:
	ds_read_b128 v[156:159], v153
	ds_read_b128 v[170:173], v153 offset:1024
	ds_read_b128 v[174:177], v153 offset:2048
	ds_read_b128 v[178:181], v153 offset:3072
	ds_read_b128 v[182:185], v154
	ds_read_b128 v[186:189], v154 offset:1024
	ds_read_b128 v[190:193], v154 offset:2048
	ds_read_b128 v[194:197], v154 offset:3072
	s_add_u32 s26, s24, 0xfffc0080
	s_addc_u32 s27, s25, -1
	s_cmp_eq_u32 s68, 12
	s_cselect_b32 s29, s17, s27
	s_cselect_b32 s28, s64, s26
	s_cselect_b32 s27, s15, s67
	s_cselect_b32 s26, s65, s66
	v_lshl_add_u64 v[142:143], s[24:25], 0, v[132:133]
	s_add_i32 m0, s23, 0xc000
	ds_read_b128 v[198:201], v155
	ds_read_b128 v[202:205], v155 offset:1024
	ds_read_b128 v[206:209], v155 offset:2048
	ds_read_b128 v[210:213], v155 offset:3072
	ds_read_b128 v[214:217], v155 offset:4096
	ds_read_b128 v[218:221], v155 offset:5120
	ds_read_b128 v[242:245], v155 offset:6144
	ds_read_b128 v[246:249], v155 offset:7168
	global_load_lds_dwordx4 v[142:143], off
	v_lshl_add_u64 v[142:143], s[24:25], 0, v[134:135]
	s_add_i32 m0, s23, 0xe000
	s_nop 0
	global_load_lds_dwordx4 v[142:143], off
	s_waitcnt vmcnt(8)
	s_waitcnt lgkmcnt(0)
	s_barrier
	s_waitcnt lgkmcnt(0)
	v_mfma_f32_16x16x32_bf16 v[124:127], v[156:159], v[198:201], v[124:127]
	v_mfma_f32_16x16x32_bf16 v[120:123], v[174:177], v[198:201], v[120:123]
	v_mfma_f32_16x16x32_bf16 v[116:119], v[156:159], v[206:209], v[116:119]
	v_mfma_f32_16x16x32_bf16 v[112:115], v[174:177], v[206:209], v[112:115]
	v_mfma_f32_16x16x32_bf16 v[108:111], v[156:159], v[214:217], v[108:111]
	v_mfma_f32_16x16x32_bf16 v[100:103], v[174:177], v[214:217], v[100:103]
	v_mfma_f32_16x16x32_bf16 v[92:95], v[156:159], v[242:245], v[92:95]
	v_mfma_f32_16x16x32_bf16 v[80:83], v[174:177], v[242:245], v[80:83]
	v_mfma_f32_16x16x32_bf16 v[124:127], v[170:173], v[202:205], v[124:127]
	v_mfma_f32_16x16x32_bf16 v[120:123], v[178:181], v[202:205], v[120:123]
	v_mfma_f32_16x16x32_bf16 v[116:119], v[170:173], v[210:213], v[116:119]
	v_mfma_f32_16x16x32_bf16 v[112:115], v[178:181], v[210:213], v[112:115]
	v_mfma_f32_16x16x32_bf16 v[108:111], v[170:173], v[218:221], v[108:111]
	v_mfma_f32_16x16x32_bf16 v[100:103], v[178:181], v[218:221], v[100:103]
	v_mfma_f32_16x16x32_bf16 v[92:95], v[170:173], v[246:249], v[92:95]
	v_mfma_f32_16x16x32_bf16 v[80:83], v[178:181], v[246:249], v[80:83]
	v_mfma_f32_16x16x32_bf16 v[104:107], v[182:185], v[198:201], v[104:107]
	v_mfma_f32_16x16x32_bf16 v[96:99], v[190:193], v[198:201], v[96:99]
	v_mfma_f32_16x16x32_bf16 v[88:91], v[182:185], v[206:209], v[88:91]
	v_mfma_f32_16x16x32_bf16 v[84:87], v[190:193], v[206:209], v[84:87]
	v_mfma_f32_16x16x32_bf16 v[76:79], v[182:185], v[214:217], v[76:79]
	v_mfma_f32_16x16x32_bf16 v[72:75], v[190:193], v[214:217], v[72:75]
	v_mfma_f32_16x16x32_bf16 v[68:71], v[182:185], v[242:245], v[68:71]
	v_mfma_f32_16x16x32_bf16 v[64:67], v[190:193], v[242:245], v[64:67]
	v_mfma_f32_16x16x32_bf16 v[104:107], v[186:189], v[202:205], v[104:107]
	v_mfma_f32_16x16x32_bf16 v[96:99], v[194:197], v[202:205], v[96:99]
	v_mfma_f32_16x16x32_bf16 v[88:91], v[186:189], v[210:213], v[88:91]
	v_mfma_f32_16x16x32_bf16 v[84:87], v[194:197], v[210:213], v[84:87]
	v_mfma_f32_16x16x32_bf16 v[76:79], v[186:189], v[218:221], v[76:79]
	v_mfma_f32_16x16x32_bf16 v[72:75], v[194:197], v[218:221], v[72:75]
	v_mfma_f32_16x16x32_bf16 v[68:71], v[186:189], v[246:249], v[68:71]
	v_mfma_f32_16x16x32_bf16 v[64:67], v[194:197], v[246:249], v[64:67]
	s_barrier
	s_add_i32 s69, s61, s30
	v_lshl_add_u64 v[142:143], s[26:27], 0, v[164:165]
	s_mov_b32 m0, s69
	ds_read_b128 v[198:201], v155 offset:16384
	ds_read_b128 v[202:205], v155 offset:17408
	ds_read_b128 v[206:209], v155 offset:18432
	ds_read_b128 v[210:213], v155 offset:19456
	ds_read_b128 v[214:217], v155 offset:20480
	ds_read_b128 v[218:221], v155 offset:21504
	ds_read_b128 v[242:245], v155 offset:22528
	ds_read_b128 v[246:249], v155 offset:23552
	global_load_lds_dwordx4 v[142:143], off
	s_add_i32 m0, s69, 0x2000
	s_add_u32 s70, s26, 0x40000
	v_lshl_add_u64 v[150:151], s[26:27], 0, v[168:169]
	s_addc_u32 s71, s27, 0
	s_add_i32 s69, s62, s30
	global_load_lds_dwordx4 v[150:151], off
	v_lshl_add_u64 v[222:223], s[70:71], 0, v[164:165]
	s_mov_b32 m0, s69
	v_lshl_add_u64 v[250:251], s[28:29], 0, v[166:167]
	global_load_lds_dwordx4 v[222:223], off
	v_lshl_add_u64 v[222:223], s[70:71], 0, v[168:169]
	s_add_i32 m0, s69, 0x2000
	s_nop 0
	global_load_lds_dwordx4 v[222:223], off
	v_lshl_add_u64 v[222:223], s[28:29], 0, v[162:163]
	s_mov_b32 m0, s23
	s_nop 0
	global_load_lds_dwordx4 v[222:223], off
	s_mov_b32 m0, s35
	s_nop 0
	global_load_lds_dwordx4 v[250:251], off
	s_waitcnt vmcnt(8)
	s_waitcnt lgkmcnt(0)
	s_barrier
; #define PG8_STAGE(bufoff, gbase, voff) do { _Pragma("unroll") for (int _i = 0; _i < 2; ++_i) \
;         __builtin_amdgcn_global_load_lds((const unsigned*)((const char*)(gbase) + (voff)[_i]), (PG8_LAS unsigned*)(lds + (bufoff) + ldsw + _i * 8192), 16, 0, 0); } while (0)
; #define PG8_LDA(dst, b, h) do { _Pragma("unroll") for (int m = 0; m < 4; ++m) _Pragma("unroll") for (int k = 0; k < 2; ++k) dst[m][k] = *(const PG8_LAS bf16x8*)(lds + PG8_SA(b, h) + aoff + m * 2048 + k * 1024); } while (0)
; #define PG8_LDB(dst, b, h) do { _Pragma("unroll") for (int n = 0; n < 2; ++n) _Pragma("unroll") for (int k = 0; k < 2; ++k) dst[n][k] = *(const PG8_LAS bf16x8*)(lds + PG8_SB(b, h) + boff + n * 2048 + k * 1024); } while (0)
; #define PG8_MMA(ai, bj, At, Bt) do { __builtin_amdgcn_s_setprio(1); _Pragma("unroll") for (int m = 0; m < 4; ++m) _Pragma("unroll") for (int n = 0; n < 2; ++n) _Pragma("unroll") for (int k = 0; k < 2; ++k) \
;         acc[ai][bj][m][n] = mma16<F16>(Bt[n][k], At[m][k], acc[ai][bj][m][n]); __builtin_amdgcn_s_setprio(0); } while (0)
; #define PG8_WAIT_V(n) asm volatile("s_waitcnt vmcnt(" #n ")" ::: "memory")
; #define PG8_WAIT_L(n) asm volatile("s_waitcnt lgkmcnt(" #n ")" ::: "memory")
; #define PG8_BAR __builtin_amdgcn_s_barrier()
; #define PG8_SCHED __builtin_amdgcn_sched_barrier(0)
; template <class Epi, class Sched, bool ALIGN_EPI = false, bool SP2 = false, bool F16 = false>
; __device__ __forceinline__ void gemm_phase(PG8_LAS unsigned char* lds, const Gemm g, const Sched& S, const Epi& E) {
;     ...
;             PG8_WAIT_V(8); PG8_WAIT_L(0); PG8_BAR; PG8_MMA(1, 0, At, B0); PG8_MMA(1, 1, At, B1); PG8_BAR; PG8_SCHED;
;             PG8_LDB(B0, 1, 0); PG8_LDB(B1, 1, 1); PG8_SCHED; PG8_LDA(At, 1, 0); PG8_STAGE(PG8_SA(0, 1), a2 + hstep, voffA);
;             PG8_WAIT_V(8); PG8_WAIT_L(0); PG8_BAR; PG8_MMA(0, 0, At, B0); PG8_MMA(0, 1, At, B1); PG8_BAR; PG8_SCHED;
	s_waitcnt lgkmcnt(0)
	v_mfma_f32_16x16x32_bf16 v[60:63], v[156:159], v[198:201], v[60:63]
	v_mfma_f32_16x16x32_bf16 v[56:59], v[174:177], v[198:201], v[56:59]
	v_mfma_f32_16x16x32_bf16 v[48:51], v[156:159], v[206:209], v[48:51]
	v_mfma_f32_16x16x32_bf16 v[40:43], v[174:177], v[206:209], v[40:43]
	v_mfma_f32_16x16x32_bf16 v[32:35], v[156:159], v[214:217], v[32:35]
	v_mfma_f32_16x16x32_bf16 v[24:27], v[174:177], v[214:217], v[24:27]
	v_mfma_f32_16x16x32_bf16 v[16:19], v[156:159], v[242:245], v[16:19]
	v_mfma_f32_16x16x32_bf16 v[8:11], v[174:177], v[242:245], v[8:11]
	v_mfma_f32_16x16x32_bf16 v[60:63], v[170:173], v[202:205], v[60:63]
	v_mfma_f32_16x16x32_bf16 v[56:59], v[178:181], v[202:205], v[56:59]
	v_mfma_f32_16x16x32_bf16 v[48:51], v[170:173], v[210:213], v[48:51]
	v_mfma_f32_16x16x32_bf16 v[40:43], v[178:181], v[210:213], v[40:43]
	v_mfma_f32_16x16x32_bf16 v[32:35], v[170:173], v[218:221], v[32:35]
	v_mfma_f32_16x16x32_bf16 v[24:27], v[178:181], v[218:221], v[24:27]
	v_mfma_f32_16x16x32_bf16 v[16:19], v[170:173], v[246:249], v[16:19]
	v_mfma_f32_16x16x32_bf16 v[8:11], v[178:181], v[246:249], v[8:11]
	v_mfma_f32_16x16x32_bf16 v[52:55], v[182:185], v[198:201], v[52:55]
	v_mfma_f32_16x16x32_bf16 v[44:47], v[190:193], v[198:201], v[44:47]
	v_mfma_f32_16x16x32_bf16 v[36:39], v[182:185], v[206:209], v[36:39]
	v_mfma_f32_16x16x32_bf16 v[28:31], v[190:193], v[206:209], v[28:31]
	v_mfma_f32_16x16x32_bf16 v[20:23], v[182:185], v[214:217], v[20:23]
	v_mfma_f32_16x16x32_bf16 v[12:15], v[190:193], v[214:217], v[12:15]
	v_mfma_f32_16x16x32_bf16 v[4:7], v[182:185], v[242:245], v[4:7]
	v_mfma_f32_16x16x32_bf16 v[0:3], v[190:193], v[242:245], v[0:3]
	v_mfma_f32_16x16x32_bf16 v[52:55], v[186:189], v[202:205], v[52:55]
	v_mfma_f32_16x16x32_bf16 v[44:47], v[194:197], v[202:205], v[44:47]
	v_mfma_f32_16x16x32_bf16 v[36:39], v[186:189], v[210:213], v[36:39]
	v_mfma_f32_16x16x32_bf16 v[28:31], v[194:197], v[210:213], v[28:31]
	v_mfma_f32_16x16x32_bf16 v[20:23], v[186:189], v[218:221], v[20:23]
	v_mfma_f32_16x16x32_bf16 v[12:15], v[194:197], v[218:221], v[12:15]
	v_mfma_f32_16x16x32_bf16 v[4:7], v[186:189], v[246:249], v[4:7]
	v_mfma_f32_16x16x32_bf16 v[0:3], v[194:197], v[246:249], v[0:3]
	s_barrier
	s_add_i32 s69, 0, 0x18000
	v_add_u32_e32 v140, s69, v147
	s_add_i32 s70, 0, 0x1c000
	ds_read_b128 v[156:159], v140
	ds_read_b128 v[170:173], v140 offset:1024
	ds_read_b128 v[174:177], v140 offset:2048
	ds_read_b128 v[178:181], v140 offset:3072
	v_add_u32_e32 v140, s70, v147
	ds_read_b128 v[182:185], v140
	ds_read_b128 v[186:189], v140 offset:1024
	ds_read_b128 v[190:193], v140 offset:2048
	ds_read_b128 v[194:197], v140 offset:3072
	s_add_u32 s28, s28, 0x40000
	s_addc_u32 s29, s29, 0
	s_mov_b32 m0, s36
	v_lshl_add_u64 v[252:253], s[28:29], 0, v[162:163]
	ds_read_b128 v[198:201], v155 offset:32768
	ds_read_b128 v[202:205], v155 offset:33792
	ds_read_b128 v[206:209], v155 offset:34816
	ds_read_b128 v[210:213], v155 offset:35840
	ds_read_b128 v[214:217], v155 offset:36864
	ds_read_b128 v[218:221], v155 offset:37888
	ds_read_b128 v[242:245], v155 offset:38912
	ds_read_b128 v[246:249], v155 offset:39936
	global_load_lds_dwordx4 v[252:253], off
	v_lshl_add_u64 v[252:253], s[28:29], 0, v[166:167]
	s_mov_b32 m0, s37
	s_nop 0
	global_load_lds_dwordx4 v[252:253], off
	s_waitcnt vmcnt(8)
	s_waitcnt lgkmcnt(0)
	s_barrier
	s_waitcnt lgkmcnt(0)
	v_mfma_f32_16x16x32_bf16 v[124:127], v[156:159], v[198:201], v[124:127]
	v_mfma_f32_16x16x32_bf16 v[120:123], v[174:177], v[198:201], v[120:123]
	v_mfma_f32_16x16x32_bf16 v[116:119], v[156:159], v[206:209], v[116:119]
	v_mfma_f32_16x16x32_bf16 v[112:115], v[174:177], v[206:209], v[112:115]
	v_mfma_f32_16x16x32_bf16 v[108:111], v[156:159], v[214:217], v[108:111]
	v_mfma_f32_16x16x32_bf16 v[100:103], v[174:177], v[214:217], v[100:103]
	v_mfma_f32_16x16x32_bf16 v[92:95], v[156:159], v[242:245], v[92:95]
	v_mfma_f32_16x16x32_bf16 v[80:83], v[174:177], v[242:245], v[80:83]
	v_mfma_f32_16x16x32_bf16 v[124:127], v[170:173], v[202:205], v[124:127]
	v_mfma_f32_16x16x32_bf16 v[120:123], v[178:181], v[202:205], v[120:123]
	v_mfma_f32_16x16x32_bf16 v[116:119], v[170:173], v[210:213], v[116:119]
	v_mfma_f32_16x16x32_bf16 v[112:115], v[178:181], v[210:213], v[112:115]
	v_mfma_f32_16x16x32_bf16 v[108:111], v[170:173], v[218:221], v[108:111]
	v_mfma_f32_16x16x32_bf16 v[100:103], v[178:181], v[218:221], v[100:103]
	v_mfma_f32_16x16x32_bf16 v[92:95], v[170:173], v[246:249], v[92:95]
	v_mfma_f32_16x16x32_bf16 v[80:83], v[178:181], v[246:249], v[80:83]
	v_mfma_f32_16x16x32_bf16 v[104:107], v[182:185], v[198:201], v[104:107]
	v_mfma_f32_16x16x32_bf16 v[96:99], v[190:193], v[198:201], v[96:99]
	v_mfma_f32_16x16x32_bf16 v[88:91], v[182:185], v[206:209], v[88:91]
	v_mfma_f32_16x16x32_bf16 v[84:87], v[190:193], v[206:209], v[84:87]
	v_mfma_f32_16x16x32_bf16 v[76:79], v[182:185], v[214:217], v[76:79]
	v_mfma_f32_16x16x32_bf16 v[72:75], v[190:193], v[214:217], v[72:75]
	v_mfma_f32_16x16x32_bf16 v[68:71], v[182:185], v[242:245], v[68:71]
	v_mfma_f32_16x16x32_bf16 v[64:67], v[190:193], v[242:245], v[64:67]
	v_mfma_f32_16x16x32_bf16 v[104:107], v[186:189], v[202:205], v[104:107]
	v_mfma_f32_16x16x32_bf16 v[96:99], v[194:197], v[202:205], v[96:99]
	v_mfma_f32_16x16x32_bf16 v[88:91], v[186:189], v[210:213], v[88:91]
	v_mfma_f32_16x16x32_bf16 v[84:87], v[194:197], v[210:213], v[84:87]
	v_mfma_f32_16x16x32_bf16 v[76:79], v[186:189], v[218:221], v[76:79]
	v_mfma_f32_16x16x32_bf16 v[72:75], v[194:197], v[218:221], v[72:75]
	v_mfma_f32_16x16x32_bf16 v[68:71], v[186:189], v[246:249], v[68:71]
	v_mfma_f32_16x16x32_bf16 v[64:67], v[194:197], v[246:249], v[64:67]
	s_barrier
; #define PG8_STAGE(bufoff, gbase, voff) do { _Pragma("unroll") for (int _i = 0; _i < 2; ++_i) \
;         __builtin_amdgcn_global_load_lds((const unsigned*)((const char*)(gbase) + (voff)[_i]), (PG8_LAS unsigned*)(lds + (bufoff) + ldsw + _i * 8192), 16, 0, 0); } while (0)
; #define PG8_LDA(dst, b, h) do { _Pragma("unroll") for (int m = 0; m < 4; ++m) _Pragma("unroll") for (int k = 0; k < 2; ++k) dst[m][k] = *(const PG8_LAS bf16x8*)(lds + PG8_SA(b, h) + aoff + m * 2048 + k * 1024); } while (0)
; #define PG8_MMA(ai, bj, At, Bt) do { __builtin_amdgcn_s_setprio(1); _Pragma("unroll") for (int m = 0; m < 4; ++m) _Pragma("unroll") for (int n = 0; n < 2; ++n) _Pragma("unroll") for (int k = 0; k < 2; ++k) \
;         acc[ai][bj][m][n] = mma16<F16>(Bt[n][k], At[m][k], acc[ai][bj][m][n]); __builtin_amdgcn_s_setprio(0); } while (0)
; #define PG8_WAIT_V(n) asm volatile("s_waitcnt vmcnt(" #n ")" ::: "memory")
; #define PG8_WAIT_L(n) asm volatile("s_waitcnt lgkmcnt(" #n ")" ::: "memory")
; #define PG8_BAR __builtin_amdgcn_s_barrier()
; #define PG8_SCHED __builtin_amdgcn_sched_barrier(0)
; template <class Epi, class Sched, bool ALIGN_EPI = false, bool SP2 = false, bool F16 = false>
; __device__ __forceinline__ void gemm_phase(PG8_LAS unsigned char* lds, const Gemm g, const Sched& S, const Epi& E) {
;     ...
;             PG8_LDA(At, 1, 1); PG8_STAGE(PG8_SB(1, 0), b3, voffB); PG8_STAGE(PG8_SB(1, 1), b3 + hstep, voffB); PG8_STAGE(PG8_SA(1, 0), a3, voffA);
;             PG8_WAIT_V(8); PG8_WAIT_L(0); PG8_BAR; PG8_MMA(1, 0, At, B0); PG8_MMA(1, 1, At, B1); PG8_BAR; PG8_SCHED;
	s_add_i32 s28, s69, s30
	v_lshl_add_u64 v[142:143], v[142:143], 0, s[10:11]
	s_mov_b32 m0, s28
	ds_read_b128 v[198:201], v155 offset:49152
	ds_read_b128 v[202:205], v155 offset:50176
	ds_read_b128 v[206:209], v155 offset:51200
	ds_read_b128 v[210:213], v155 offset:52224
	ds_read_b128 v[214:217], v155 offset:53248
	ds_read_b128 v[218:221], v155 offset:54272
	ds_read_b128 v[242:245], v155 offset:55296
	ds_read_b128 v[246:249], v155 offset:56320
	global_load_lds_dwordx4 v[142:143], off
	s_add_i32 m0, s28, 0x2000
	s_add_u32 s26, s26, 0x40080
	v_lshl_add_u64 v[142:143], v[150:151], 0, s[10:11]
	s_addc_u32 s27, s27, 0
	s_add_i32 s28, s70, s30
	global_load_lds_dwordx4 v[142:143], off
	v_lshl_add_u64 v[142:143], s[26:27], 0, v[164:165]
	s_mov_b32 m0, s28
	s_nop 0
	global_load_lds_dwordx4 v[142:143], off
	v_lshl_add_u64 v[142:143], s[26:27], 0, v[168:169]
	s_add_i32 m0, s28, 0x2000
	s_nop 0
	global_load_lds_dwordx4 v[142:143], off
	v_lshl_add_u64 v[142:143], v[222:223], 0, s[10:11]
	s_mov_b32 m0, s39
	s_nop 0
	global_load_lds_dwordx4 v[142:143], off
	v_lshl_add_u64 v[142:143], v[250:251], 0, s[10:11]
	s_mov_b32 m0, s54
	s_nop 0
	global_load_lds_dwordx4 v[142:143], off
	s_waitcnt vmcnt(8)
	s_waitcnt lgkmcnt(0)
	s_barrier
	s_waitcnt lgkmcnt(0)
	v_mfma_f32_16x16x32_bf16 v[60:63], v[156:159], v[198:201], v[60:63]
	v_mfma_f32_16x16x32_bf16 v[56:59], v[174:177], v[198:201], v[56:59]
	v_mfma_f32_16x16x32_bf16 v[48:51], v[156:159], v[206:209], v[48:51]
	v_mfma_f32_16x16x32_bf16 v[40:43], v[174:177], v[206:209], v[40:43]
	v_mfma_f32_16x16x32_bf16 v[32:35], v[156:159], v[214:217], v[32:35]
	v_mfma_f32_16x16x32_bf16 v[24:27], v[174:177], v[214:217], v[24:27]
	v_mfma_f32_16x16x32_bf16 v[16:19], v[156:159], v[242:245], v[16:19]
	v_mfma_f32_16x16x32_bf16 v[8:11], v[174:177], v[242:245], v[8:11]
	v_mfma_f32_16x16x32_bf16 v[60:63], v[170:173], v[202:205], v[60:63]
	v_mfma_f32_16x16x32_bf16 v[56:59], v[178:181], v[202:205], v[56:59]
	v_mfma_f32_16x16x32_bf16 v[48:51], v[170:173], v[210:213], v[48:51]
	v_mfma_f32_16x16x32_bf16 v[40:43], v[178:181], v[210:213], v[40:43]
	v_mfma_f32_16x16x32_bf16 v[32:35], v[170:173], v[218:221], v[32:35]
	v_mfma_f32_16x16x32_bf16 v[24:27], v[178:181], v[218:221], v[24:27]
	v_mfma_f32_16x16x32_bf16 v[16:19], v[170:173], v[246:249], v[16:19]
	v_mfma_f32_16x16x32_bf16 v[8:11], v[178:181], v[246:249], v[8:11]
	v_mfma_f32_16x16x32_bf16 v[52:55], v[182:185], v[198:201], v[52:55]
	v_mfma_f32_16x16x32_bf16 v[44:47], v[190:193], v[198:201], v[44:47]
	v_mfma_f32_16x16x32_bf16 v[36:39], v[182:185], v[206:209], v[36:39]
	v_mfma_f32_16x16x32_bf16 v[28:31], v[190:193], v[206:209], v[28:31]
	v_mfma_f32_16x16x32_bf16 v[20:23], v[182:185], v[214:217], v[20:23]
	v_mfma_f32_16x16x32_bf16 v[12:15], v[190:193], v[214:217], v[12:15]
	v_mfma_f32_16x16x32_bf16 v[4:7], v[182:185], v[242:245], v[4:7]
	v_mfma_f32_16x16x32_bf16 v[0:3], v[190:193], v[242:245], v[0:3]
	v_mfma_f32_16x16x32_bf16 v[52:55], v[186:189], v[202:205], v[52:55]
	v_mfma_f32_16x16x32_bf16 v[44:47], v[194:197], v[202:205], v[44:47]
	v_mfma_f32_16x16x32_bf16 v[36:39], v[186:189], v[210:213], v[36:39]
	v_mfma_f32_16x16x32_bf16 v[28:31], v[194:197], v[210:213], v[28:31]
	v_mfma_f32_16x16x32_bf16 v[20:23], v[186:189], v[218:221], v[20:23]
	v_mfma_f32_16x16x32_bf16 v[12:15], v[194:197], v[218:221], v[12:15]
	v_mfma_f32_16x16x32_bf16 v[4:7], v[186:189], v[246:249], v[4:7]
	v_mfma_f32_16x16x32_bf16 v[0:3], v[194:197], v[246:249], v[0:3]
	s_barrier
	s_add_i32 s68, s68, 2
	s_add_u32 s24, s24, 0x100
	s_addc_u32 s25, s25, 0
	s_add_u32 s66, s66, 0x100
	s_addc_u32 s67, s67, 0
	s_cmp_gt_u32 s68, 13
	s_cbranch_scc0 .LBB0_178
	s_and_b64 vcc, exec, s[12:13]
	s_cbranch_vccz .LBB0_181
	s_barrier

; #define PG8_STAGE(bufoff, gbase, voff) do { _Pragma("unroll") for (int _i = 0; _i < 2; ++_i) \
;         __builtin_amdgcn_global_load_lds((const unsigned*)((const char*)(gbase) + (voff)[_i]), (PG8_LAS unsigned*)(lds + (bufoff) + ldsw + _i * 8192), 16, 0, 0); } while (0)
; #define PG8_LDA(dst, b, h) do { _Pragma("unroll") for (int m = 0; m < 4; ++m) _Pragma("unroll") for (int k = 0; k < 2; ++k) dst[m][k] = *(const PG8_LAS bf16x8*)(lds + PG8_SA(b, h) + aoff + m * 2048 + k * 1024); } while (0)
; #define PG8_LDB(dst, b, h) do { _Pragma("unroll") for (int n = 0; n < 2; ++n) _Pragma("unroll") for (int k = 0; k < 2; ++k) dst[n][k] = *(const PG8_LAS bf16x8*)(lds + PG8_SB(b, h) + boff + n * 2048 + k * 1024); } while (0)
; #define PG8_MMA(ai, bj, At, Bt) do { __builtin_amdgcn_s_setprio(1); _Pragma("unroll") for (int m = 0; m < 4; ++m) _Pragma("unroll") for (int n = 0; n < 2; ++n) _Pragma("unroll") for (int k = 0; k < 2; ++k) \
;         acc[ai][bj][m][n] = mma16<F16>(Bt[n][k], At[m][k], acc[ai][bj][m][n]); __builtin_amdgcn_s_setprio(0); } while (0)
; #define PG8_WAIT_V(n) asm volatile("s_waitcnt vmcnt(" #n ")" ::: "memory")
; #define PG8_WAIT_L(n) asm volatile("s_waitcnt lgkmcnt(" #n ")" ::: "memory")
; #define PG8_BAR __builtin_amdgcn_s_barrier()
; #define PG8_SCHED __builtin_amdgcn_sched_barrier(0)
; template <class Epi, class Sched, bool ALIGN_EPI = false, bool SP2 = false, bool F16 = false>
; __device__ __forceinline__ void gemm_phase(PG8_LAS unsigned char* lds, const Gemm g, const Sched& S, const Epi& E) {
;     ...
;             PG8_LDB(B0, 0, 0); PG8_LDB(B1, 0, 1); PG8_SCHED; PG8_LDA(At, 0, 0); PG8_STAGE(PG8_SA(1, 1), a1 + hstep, voffA);
;             PG8_WAIT_V(8); PG8_WAIT_L(0); PG8_BAR; PG8_MMA(0, 0, At, B0); PG8_MMA(0, 1, At, B1); PG8_BAR; PG8_SCHED;
;             PG8_LDA(At, 0, 1); PG8_STAGE(PG8_SB(0, 0), b2, voffB); PG8_STAGE(PG8_SB(0, 1), b2 + hstep, voffB); PG8_STAGE(PG8_SA(0, 0), a2, voffA);
;             PG8_WAIT_V(8); PG8_WAIT_L(0); PG8_BAR; PG8_MMA(1, 0, At, B0); PG8_MMA(1, 1, At, B1); PG8_BAR; PG8_SCHED;
.LBB0_412:
	ds_read_b128 v[146:149], v141
	ds_read_b128 v[150:153], v141 offset:1024
	ds_read_b128 v[154:157], v141 offset:2048
	ds_read_b128 v[170:173], v141 offset:3072
	ds_read_b128 v[174:177], v142
	ds_read_b128 v[178:181], v142 offset:1024
	ds_read_b128 v[182:185], v142 offset:2048
	ds_read_b128 v[186:189], v142 offset:3072
	s_add_u32 s30, s28, 0xfffc0080
	s_addc_u32 s31, s29, -1
	s_cmp_eq_u32 s70, 12
	s_cselect_b32 s35, s19, s31
	s_cselect_b32 s34, s25, s30
	s_cselect_b32 s31, s17, s69
	s_cselect_b32 s30, s67, s68
	v_lshl_add_u64 v[136:137], s[28:29], 0, v[128:129]
	s_add_i32 m0, s27, 0xc000
	ds_read_b128 v[190:193], v143
	ds_read_b128 v[194:197], v143 offset:1024
	ds_read_b128 v[198:201], v143 offset:2048
	ds_read_b128 v[206:209], v143 offset:3072
	ds_read_b128 v[210:213], v143 offset:4096
	ds_read_b128 v[214:217], v143 offset:5120
	ds_read_b128 v[218:221], v143 offset:6144
	ds_read_b128 v[240:243], v143 offset:7168
	global_load_lds_dwordx4 v[136:137], off
	v_lshl_add_u64 v[136:137], s[28:29], 0, v[130:131]
	s_add_i32 m0, s27, 0xe000
	s_nop 0
	global_load_lds_dwordx4 v[136:137], off
	s_waitcnt vmcnt(8)
	s_waitcnt lgkmcnt(0)
	s_barrier
	s_waitcnt lgkmcnt(0)
	v_mfma_f32_16x16x32_bf16 v[124:127], v[146:149], v[190:193], v[124:127]
	v_mfma_f32_16x16x32_bf16 v[116:119], v[154:157], v[190:193], v[116:119]
	v_mfma_f32_16x16x32_bf16 v[108:111], v[146:149], v[198:201], v[108:111]
	v_mfma_f32_16x16x32_bf16 v[100:103], v[154:157], v[198:201], v[100:103]
	v_mfma_f32_16x16x32_bf16 v[92:95], v[146:149], v[210:213], v[92:95]
	v_mfma_f32_16x16x32_bf16 v[84:87], v[154:157], v[210:213], v[84:87]
	v_mfma_f32_16x16x32_bf16 v[76:79], v[146:149], v[218:221], v[76:79]
	v_mfma_f32_16x16x32_bf16 v[68:71], v[154:157], v[218:221], v[68:71]
	v_mfma_f32_16x16x32_bf16 v[124:127], v[150:153], v[194:197], v[124:127]
	v_mfma_f32_16x16x32_bf16 v[116:119], v[170:173], v[194:197], v[116:119]
	v_mfma_f32_16x16x32_bf16 v[108:111], v[150:153], v[206:209], v[108:111]
	v_mfma_f32_16x16x32_bf16 v[100:103], v[170:173], v[206:209], v[100:103]
	v_mfma_f32_16x16x32_bf16 v[92:95], v[150:153], v[214:217], v[92:95]
	v_mfma_f32_16x16x32_bf16 v[84:87], v[170:173], v[214:217], v[84:87]
	v_mfma_f32_16x16x32_bf16 v[76:79], v[150:153], v[240:243], v[76:79]
	v_mfma_f32_16x16x32_bf16 v[68:71], v[170:173], v[240:243], v[68:71]
	v_mfma_f32_16x16x32_bf16 v[120:123], v[174:177], v[190:193], v[120:123]
	v_mfma_f32_16x16x32_bf16 v[112:115], v[182:185], v[190:193], v[112:115]
	v_mfma_f32_16x16x32_bf16 v[104:107], v[174:177], v[198:201], v[104:107]
	v_mfma_f32_16x16x32_bf16 v[96:99], v[182:185], v[198:201], v[96:99]
	v_mfma_f32_16x16x32_bf16 v[88:91], v[174:177], v[210:213], v[88:91]
	v_mfma_f32_16x16x32_bf16 v[80:83], v[182:185], v[210:213], v[80:83]
	v_mfma_f32_16x16x32_bf16 v[72:75], v[174:177], v[218:221], v[72:75]
	v_mfma_f32_16x16x32_bf16 v[64:67], v[182:185], v[218:221], v[64:67]
	v_mfma_f32_16x16x32_bf16 v[120:123], v[178:181], v[194:197], v[120:123]
	v_mfma_f32_16x16x32_bf16 v[112:115], v[186:189], v[194:197], v[112:115]
	v_mfma_f32_16x16x32_bf16 v[104:107], v[178:181], v[206:209], v[104:107]
	v_mfma_f32_16x16x32_bf16 v[96:99], v[186:189], v[206:209], v[96:99]
	v_mfma_f32_16x16x32_bf16 v[88:91], v[178:181], v[214:217], v[88:91]
	v_mfma_f32_16x16x32_bf16 v[80:83], v[186:189], v[214:217], v[80:83]
	v_mfma_f32_16x16x32_bf16 v[72:75], v[178:181], v[240:243], v[72:75]
	v_mfma_f32_16x16x32_bf16 v[64:67], v[186:189], v[240:243], v[64:67]
	s_barrier
	s_add_i32 s71, s65, s37
	v_lshl_add_u64 v[136:137], s[30:31], 0, v[164:165]
	s_mov_b32 m0, s71
	ds_read_b128 v[190:193], v143 offset:16384
	ds_read_b128 v[194:197], v143 offset:17408
	ds_read_b128 v[198:201], v143 offset:18432
	ds_read_b128 v[206:209], v143 offset:19456
	ds_read_b128 v[210:213], v143 offset:20480
	ds_read_b128 v[214:217], v143 offset:21504
	ds_read_b128 v[218:221], v143 offset:22528
	ds_read_b128 v[240:243], v143 offset:23552
	global_load_lds_dwordx4 v[136:137], off
	s_add_i32 m0, s71, 0x2000
	s_add_u32 s72, s30, 0x40000
	v_lshl_add_u64 v[158:159], s[30:31], 0, v[168:169]
	s_addc_u32 s73, s31, 0
	s_add_i32 s71, s66, s37
	global_load_lds_dwordx4 v[158:159], off
	v_lshl_add_u64 v[222:223], s[72:73], 0, v[164:165]
	s_mov_b32 m0, s71
	v_lshl_add_u64 v[244:245], s[34:35], 0, v[166:167]
	global_load_lds_dwordx4 v[222:223], off
	v_lshl_add_u64 v[222:223], s[72:73], 0, v[168:169]
	s_add_i32 m0, s71, 0x2000
	s_nop 0
	global_load_lds_dwordx4 v[222:223], off
	v_lshl_add_u64 v[222:223], s[34:35], 0, v[162:163]
	s_mov_b32 m0, s27
	s_nop 0
	global_load_lds_dwordx4 v[222:223], off
	s_mov_b32 m0, s38
	s_nop 0
	global_load_lds_dwordx4 v[244:245], off
	s_waitcnt vmcnt(8)
	s_waitcnt lgkmcnt(0)
	s_barrier
; #define PG8_STAGE(bufoff, gbase, voff) do { _Pragma("unroll") for (int _i = 0; _i < 2; ++_i) \
;         __builtin_amdgcn_global_load_lds((const unsigned*)((const char*)(gbase) + (voff)[_i]), (PG8_LAS unsigned*)(lds + (bufoff) + ldsw + _i * 8192), 16, 0, 0); } while (0)
; #define PG8_LDA(dst, b, h) do { _Pragma("unroll") for (int m = 0; m < 4; ++m) _Pragma("unroll") for (int k = 0; k < 2; ++k) dst[m][k] = *(const PG8_LAS bf16x8*)(lds + PG8_SA(b, h) + aoff + m * 2048 + k * 1024); } while (0)
; #define PG8_LDB(dst, b, h) do { _Pragma("unroll") for (int n = 0; n < 2; ++n) _Pragma("unroll") for (int k = 0; k < 2; ++k) dst[n][k] = *(const PG8_LAS bf16x8*)(lds + PG8_SB(b, h) + boff + n * 2048 + k * 1024); } while (0)
; #define PG8_MMA(ai, bj, At, Bt) do { __builtin_amdgcn_s_setprio(1); _Pragma("unroll") for (int m = 0; m < 4; ++m) _Pragma("unroll") for (int n = 0; n < 2; ++n) _Pragma("unroll") for (int k = 0; k < 2; ++k) \
;         acc[ai][bj][m][n] = mma16<F16>(Bt[n][k], At[m][k], acc[ai][bj][m][n]); __builtin_amdgcn_s_setprio(0); } while (0)
; #define PG8_WAIT_V(n) asm volatile("s_waitcnt vmcnt(" #n ")" ::: "memory")
; #define PG8_WAIT_L(n) asm volatile("s_waitcnt lgkmcnt(" #n ")" ::: "memory")
; #define PG8_BAR __builtin_amdgcn_s_barrier()
; #define PG8_SCHED __builtin_amdgcn_sched_barrier(0)
; template <class Epi, class Sched, bool ALIGN_EPI = false, bool SP2 = false, bool F16 = false>
; __device__ __forceinline__ void gemm_phase(PG8_LAS unsigned char* lds, const Gemm g, const Sched& S, const Epi& E) {
;     ...
;             PG8_WAIT_V(8); PG8_WAIT_L(0); PG8_BAR; PG8_MMA(1, 0, At, B0); PG8_MMA(1, 1, At, B1); PG8_BAR; PG8_SCHED;
;             PG8_LDB(B0, 1, 0); PG8_LDB(B1, 1, 1); PG8_SCHED; PG8_LDA(At, 1, 0); PG8_STAGE(PG8_SA(0, 1), a2 + hstep, voffA);
;             PG8_WAIT_V(8); PG8_WAIT_L(0); PG8_BAR; PG8_MMA(0, 0, At, B0); PG8_MMA(0, 1, At, B1); PG8_BAR; PG8_SCHED;
	s_waitcnt lgkmcnt(0)
	v_mfma_f32_16x16x32_bf16 v[60:63], v[146:149], v[190:193], v[60:63]
	v_mfma_f32_16x16x32_bf16 v[52:55], v[154:157], v[190:193], v[52:55]
	v_mfma_f32_16x16x32_bf16 v[44:47], v[146:149], v[198:201], v[44:47]
	v_mfma_f32_16x16x32_bf16 v[36:39], v[154:157], v[198:201], v[36:39]
	v_mfma_f32_16x16x32_bf16 v[28:31], v[146:149], v[210:213], v[28:31]
	v_mfma_f32_16x16x32_bf16 v[20:23], v[154:157], v[210:213], v[20:23]
	v_mfma_f32_16x16x32_bf16 v[12:15], v[146:149], v[218:221], v[12:15]
	v_mfma_f32_16x16x32_bf16 v[4:7], v[154:157], v[218:221], v[4:7]
	v_mfma_f32_16x16x32_bf16 v[60:63], v[150:153], v[194:197], v[60:63]
	v_mfma_f32_16x16x32_bf16 v[52:55], v[170:173], v[194:197], v[52:55]
	v_mfma_f32_16x16x32_bf16 v[44:47], v[150:153], v[206:209], v[44:47]
	v_mfma_f32_16x16x32_bf16 v[36:39], v[170:173], v[206:209], v[36:39]
	v_mfma_f32_16x16x32_bf16 v[28:31], v[150:153], v[214:217], v[28:31]
	v_mfma_f32_16x16x32_bf16 v[20:23], v[170:173], v[214:217], v[20:23]
	v_mfma_f32_16x16x32_bf16 v[12:15], v[150:153], v[240:243], v[12:15]
	v_mfma_f32_16x16x32_bf16 v[4:7], v[170:173], v[240:243], v[4:7]
	v_mfma_f32_16x16x32_bf16 v[56:59], v[174:177], v[190:193], v[56:59]
	v_mfma_f32_16x16x32_bf16 v[48:51], v[182:185], v[190:193], v[48:51]
	v_mfma_f32_16x16x32_bf16 v[40:43], v[174:177], v[198:201], v[40:43]
	v_mfma_f32_16x16x32_bf16 v[32:35], v[182:185], v[198:201], v[32:35]
	v_mfma_f32_16x16x32_bf16 v[24:27], v[174:177], v[210:213], v[24:27]
	v_mfma_f32_16x16x32_bf16 v[16:19], v[182:185], v[210:213], v[16:19]
	v_mfma_f32_16x16x32_bf16 v[8:11], v[174:177], v[218:221], v[8:11]
	v_mfma_f32_16x16x32_bf16 v[0:3], v[182:185], v[218:221], v[0:3]
	v_mfma_f32_16x16x32_bf16 v[56:59], v[178:181], v[194:197], v[56:59]
	v_mfma_f32_16x16x32_bf16 v[48:51], v[186:189], v[194:197], v[48:51]
	v_mfma_f32_16x16x32_bf16 v[40:43], v[178:181], v[206:209], v[40:43]
	v_mfma_f32_16x16x32_bf16 v[32:35], v[186:189], v[206:209], v[32:35]
	v_mfma_f32_16x16x32_bf16 v[24:27], v[178:181], v[214:217], v[24:27]
	v_mfma_f32_16x16x32_bf16 v[16:19], v[186:189], v[214:217], v[16:19]
	v_mfma_f32_16x16x32_bf16 v[8:11], v[178:181], v[240:243], v[8:11]
	v_mfma_f32_16x16x32_bf16 v[0:3], v[186:189], v[240:243], v[0:3]
	s_barrier
	s_add_i32 s71, 0, 0x18000
	v_add_u32_e32 v145, s71, v139
	s_add_i32 s72, 0, 0x1c000
	ds_read_b128 v[146:149], v145
	ds_read_b128 v[150:153], v145 offset:1024
	ds_read_b128 v[154:157], v145 offset:2048
	ds_read_b128 v[170:173], v145 offset:3072
	v_add_u32_e32 v145, s72, v139
	ds_read_b128 v[174:177], v145
	ds_read_b128 v[178:181], v145 offset:1024
	ds_read_b128 v[182:185], v145 offset:2048
	ds_read_b128 v[186:189], v145 offset:3072
	s_add_u32 s34, s34, 0x40000
	s_addc_u32 s35, s35, 0
	s_mov_b32 m0, s39
	v_lshl_add_u64 v[246:247], s[34:35], 0, v[162:163]
	ds_read_b128 v[190:193], v143 offset:32768
	ds_read_b128 v[194:197], v143 offset:33792
	ds_read_b128 v[198:201], v143 offset:34816
	ds_read_b128 v[206:209], v143 offset:35840
	ds_read_b128 v[210:213], v143 offset:36864
	ds_read_b128 v[214:217], v143 offset:37888
	ds_read_b128 v[218:221], v143 offset:38912
	ds_read_b128 v[240:243], v143 offset:39936
	global_load_lds_dwordx4 v[246:247], off
	v_lshl_add_u64 v[246:247], s[34:35], 0, v[166:167]
	s_mov_b32 m0, s40
	s_nop 0
	global_load_lds_dwordx4 v[246:247], off
	s_waitcnt vmcnt(8)
	s_waitcnt lgkmcnt(0)
	s_barrier
	s_waitcnt lgkmcnt(0)
	v_mfma_f32_16x16x32_bf16 v[124:127], v[146:149], v[190:193], v[124:127]
	v_mfma_f32_16x16x32_bf16 v[116:119], v[154:157], v[190:193], v[116:119]
	v_mfma_f32_16x16x32_bf16 v[108:111], v[146:149], v[198:201], v[108:111]
	v_mfma_f32_16x16x32_bf16 v[100:103], v[154:157], v[198:201], v[100:103]
	v_mfma_f32_16x16x32_bf16 v[92:95], v[146:149], v[210:213], v[92:95]
	v_mfma_f32_16x16x32_bf16 v[84:87], v[154:157], v[210:213], v[84:87]
	v_mfma_f32_16x16x32_bf16 v[76:79], v[146:149], v[218:221], v[76:79]
	v_mfma_f32_16x16x32_bf16 v[68:71], v[154:157], v[218:221], v[68:71]
	v_mfma_f32_16x16x32_bf16 v[124:127], v[150:153], v[194:197], v[124:127]
	v_mfma_f32_16x16x32_bf16 v[116:119], v[170:173], v[194:197], v[116:119]
	v_mfma_f32_16x16x32_bf16 v[108:111], v[150:153], v[206:209], v[108:111]
	v_mfma_f32_16x16x32_bf16 v[100:103], v[170:173], v[206:209], v[100:103]
	v_mfma_f32_16x16x32_bf16 v[92:95], v[150:153], v[214:217], v[92:95]
	v_mfma_f32_16x16x32_bf16 v[84:87], v[170:173], v[214:217], v[84:87]
	v_mfma_f32_16x16x32_bf16 v[76:79], v[150:153], v[240:243], v[76:79]
	v_mfma_f32_16x16x32_bf16 v[68:71], v[170:173], v[240:243], v[68:71]
	v_mfma_f32_16x16x32_bf16 v[120:123], v[174:177], v[190:193], v[120:123]
	v_mfma_f32_16x16x32_bf16 v[112:115], v[182:185], v[190:193], v[112:115]
	v_mfma_f32_16x16x32_bf16 v[104:107], v[174:177], v[198:201], v[104:107]
	v_mfma_f32_16x16x32_bf16 v[96:99], v[182:185], v[198:201], v[96:99]
	v_mfma_f32_16x16x32_bf16 v[88:91], v[174:177], v[210:213], v[88:91]
	v_mfma_f32_16x16x32_bf16 v[80:83], v[182:185], v[210:213], v[80:83]
	v_mfma_f32_16x16x32_bf16 v[72:75], v[174:177], v[218:221], v[72:75]
	v_mfma_f32_16x16x32_bf16 v[64:67], v[182:185], v[218:221], v[64:67]
	v_mfma_f32_16x16x32_bf16 v[120:123], v[178:181], v[194:197], v[120:123]
	v_mfma_f32_16x16x32_bf16 v[112:115], v[186:189], v[194:197], v[112:115]
	v_mfma_f32_16x16x32_bf16 v[104:107], v[178:181], v[206:209], v[104:107]
	v_mfma_f32_16x16x32_bf16 v[96:99], v[186:189], v[206:209], v[96:99]
	v_mfma_f32_16x16x32_bf16 v[88:91], v[178:181], v[214:217], v[88:91]
	v_mfma_f32_16x16x32_bf16 v[80:83], v[186:189], v[214:217], v[80:83]
	v_mfma_f32_16x16x32_bf16 v[72:75], v[178:181], v[240:243], v[72:75]
	v_mfma_f32_16x16x32_bf16 v[64:67], v[186:189], v[240:243], v[64:67]
	s_barrier
; #define PG8_STAGE(bufoff, gbase, voff) do { _Pragma("unroll") for (int _i = 0; _i < 2; ++_i) \
;         __builtin_amdgcn_global_load_lds((const unsigned*)((const char*)(gbase) + (voff)[_i]), (PG8_LAS unsigned*)(lds + (bufoff) + ldsw + _i * 8192), 16, 0, 0); } while (0)
; #define PG8_LDA(dst, b, h) do { _Pragma("unroll") for (int m = 0; m < 4; ++m) _Pragma("unroll") for (int k = 0; k < 2; ++k) dst[m][k] = *(const PG8_LAS bf16x8*)(lds + PG8_SA(b, h) + aoff + m * 2048 + k * 1024); } while (0)
; #define PG8_MMA(ai, bj, At, Bt) do { __builtin_amdgcn_s_setprio(1); _Pragma("unroll") for (int m = 0; m < 4; ++m) _Pragma("unroll") for (int n = 0; n < 2; ++n) _Pragma("unroll") for (int k = 0; k < 2; ++k) \
;         acc[ai][bj][m][n] = mma16<F16>(Bt[n][k], At[m][k], acc[ai][bj][m][n]); __builtin_amdgcn_s_setprio(0); } while (0)
; #define PG8_WAIT_V(n) asm volatile("s_waitcnt vmcnt(" #n ")" ::: "memory")
; #define PG8_WAIT_L(n) asm volatile("s_waitcnt lgkmcnt(" #n ")" ::: "memory")
; #define PG8_BAR __builtin_amdgcn_s_barrier()
; #define PG8_SCHED __builtin_amdgcn_sched_barrier(0)
; template <class Epi, class Sched, bool ALIGN_EPI = false, bool SP2 = false, bool F16 = false>
; __device__ __forceinline__ void gemm_phase(PG8_LAS unsigned char* lds, const Gemm g, const Sched& S, const Epi& E) {
;     ...
;             PG8_LDA(At, 1, 1); PG8_STAGE(PG8_SB(1, 0), b3, voffB); PG8_STAGE(PG8_SB(1, 1), b3 + hstep, voffB); PG8_STAGE(PG8_SA(1, 0), a3, voffA);
;             PG8_WAIT_V(8); PG8_WAIT_L(0); PG8_BAR; PG8_MMA(1, 0, At, B0); PG8_MMA(1, 1, At, B1); PG8_BAR; PG8_SCHED;
	s_add_i32 s34, s71, s37
	v_lshl_add_u64 v[136:137], v[136:137], 0, s[12:13]
	s_mov_b32 m0, s34
	ds_read_b128 v[190:193], v143 offset:49152
	ds_read_b128 v[194:197], v143 offset:50176
	ds_read_b128 v[198:201], v143 offset:51200
	ds_read_b128 v[206:209], v143 offset:52224
	ds_read_b128 v[210:213], v143 offset:53248
	ds_read_b128 v[214:217], v143 offset:54272
	ds_read_b128 v[218:221], v143 offset:55296
	ds_read_b128 v[240:243], v143 offset:56320
	global_load_lds_dwordx4 v[136:137], off
	s_add_i32 m0, s34, 0x2000
	s_add_u32 s30, s30, 0x40080
	v_lshl_add_u64 v[136:137], v[158:159], 0, s[12:13]
	s_addc_u32 s31, s31, 0
	s_add_i32 s34, s72, s37
	global_load_lds_dwordx4 v[136:137], off
	v_lshl_add_u64 v[136:137], s[30:31], 0, v[164:165]
	s_mov_b32 m0, s34
	s_nop 0
	global_load_lds_dwordx4 v[136:137], off
	v_lshl_add_u64 v[136:137], s[30:31], 0, v[168:169]
	s_add_i32 m0, s34, 0x2000
	s_nop 0
	global_load_lds_dwordx4 v[136:137], off
	v_lshl_add_u64 v[136:137], v[222:223], 0, s[12:13]
	s_mov_b32 m0, s42
	s_nop 0
	global_load_lds_dwordx4 v[136:137], off
	v_lshl_add_u64 v[136:137], v[244:245], 0, s[12:13]
	s_mov_b32 m0, s43
	s_nop 0
	global_load_lds_dwordx4 v[136:137], off
	s_waitcnt vmcnt(8)
	s_waitcnt lgkmcnt(0)
	s_barrier
	s_waitcnt lgkmcnt(0)
	v_mfma_f32_16x16x32_bf16 v[60:63], v[146:149], v[190:193], v[60:63]
	v_mfma_f32_16x16x32_bf16 v[52:55], v[154:157], v[190:193], v[52:55]
	v_mfma_f32_16x16x32_bf16 v[44:47], v[146:149], v[198:201], v[44:47]
	v_mfma_f32_16x16x32_bf16 v[36:39], v[154:157], v[198:201], v[36:39]
	v_mfma_f32_16x16x32_bf16 v[28:31], v[146:149], v[210:213], v[28:31]
	v_mfma_f32_16x16x32_bf16 v[20:23], v[154:157], v[210:213], v[20:23]
	v_mfma_f32_16x16x32_bf16 v[12:15], v[146:149], v[218:221], v[12:15]
	v_mfma_f32_16x16x32_bf16 v[4:7], v[154:157], v[218:221], v[4:7]
	v_mfma_f32_16x16x32_bf16 v[60:63], v[150:153], v[194:197], v[60:63]
	v_mfma_f32_16x16x32_bf16 v[52:55], v[170:173], v[194:197], v[52:55]
	v_mfma_f32_16x16x32_bf16 v[44:47], v[150:153], v[206:209], v[44:47]
	v_mfma_f32_16x16x32_bf16 v[36:39], v[170:173], v[206:209], v[36:39]
	v_mfma_f32_16x16x32_bf16 v[28:31], v[150:153], v[214:217], v[28:31]
	v_mfma_f32_16x16x32_bf16 v[20:23], v[170:173], v[214:217], v[20:23]
	v_mfma_f32_16x16x32_bf16 v[12:15], v[150:153], v[240:243], v[12:15]
	v_mfma_f32_16x16x32_bf16 v[4:7], v[170:173], v[240:243], v[4:7]
	v_mfma_f32_16x16x32_bf16 v[56:59], v[174:177], v[190:193], v[56:59]
	v_mfma_f32_16x16x32_bf16 v[48:51], v[182:185], v[190:193], v[48:51]
	v_mfma_f32_16x16x32_bf16 v[40:43], v[174:177], v[198:201], v[40:43]
	v_mfma_f32_16x16x32_bf16 v[32:35], v[182:185], v[198:201], v[32:35]
	v_mfma_f32_16x16x32_bf16 v[24:27], v[174:177], v[210:213], v[24:27]
	v_mfma_f32_16x16x32_bf16 v[16:19], v[182:185], v[210:213], v[16:19]
	v_mfma_f32_16x16x32_bf16 v[8:11], v[174:177], v[218:221], v[8:11]
	v_mfma_f32_16x16x32_bf16 v[0:3], v[182:185], v[218:221], v[0:3]
	v_mfma_f32_16x16x32_bf16 v[56:59], v[178:181], v[194:197], v[56:59]
	v_mfma_f32_16x16x32_bf16 v[48:51], v[186:189], v[194:197], v[48:51]
	v_mfma_f32_16x16x32_bf16 v[40:43], v[178:181], v[206:209], v[40:43]
	v_mfma_f32_16x16x32_bf16 v[32:35], v[186:189], v[206:209], v[32:35]
	v_mfma_f32_16x16x32_bf16 v[24:27], v[178:181], v[214:217], v[24:27]
	v_mfma_f32_16x16x32_bf16 v[16:19], v[186:189], v[214:217], v[16:19]
	v_mfma_f32_16x16x32_bf16 v[8:11], v[178:181], v[240:243], v[8:11]
	v_mfma_f32_16x16x32_bf16 v[0:3], v[186:189], v[240:243], v[0:3]
	s_barrier
	s_add_i32 s70, s70, 2
	s_add_u32 s28, s28, 0x100
	s_addc_u32 s29, s29, 0
	s_add_u32 s68, s68, 0x100
	s_addc_u32 s69, s69, 0
	s_cmp_gt_u32 s70, 13
	s_cbranch_scc0 .LBB0_412
	s_and_b64 vcc, exec, s[14:15]
	s_cbranch_vccz .LBB0_415
	s_barrier

; #define PG8_STAGE(bufoff, gbase, voff) do { _Pragma("unroll") for (int _i = 0; _i < 2; ++_i) \
;         __builtin_amdgcn_global_load_lds((const unsigned*)((const char*)(gbase) + (voff)[_i]), (PG8_LAS unsigned*)(lds + (bufoff) + ldsw + _i * 8192), 16, 0, 0); } while (0)
; #define PG8_LDA(dst, b, h) do { _Pragma("unroll") for (int m = 0; m < 4; ++m) _Pragma("unroll") for (int k = 0; k < 2; ++k) dst[m][k] = *(const PG8_LAS bf16x8*)(lds + PG8_SA(b, h) + aoff + m * 2048 + k * 1024); } while (0)
; #define PG8_LDB(dst, b, h) do { _Pragma("unroll") for (int n = 0; n < 2; ++n) _Pragma("unroll") for (int k = 0; k < 2; ++k) dst[n][k] = *(const PG8_LAS bf16x8*)(lds + PG8_SB(b, h) + boff + n * 2048 + k * 1024); } while (0)
; #define PG8_MMA(ai, bj, At, Bt) do { __builtin_amdgcn_s_setprio(1); _Pragma("unroll") for (int m = 0; m < 4; ++m) _Pragma("unroll") for (int n = 0; n < 2; ++n) _Pragma("unroll") for (int k = 0; k < 2; ++k) \
;         acc[ai][bj][m][n] = mma16<F16>(Bt[n][k], At[m][k], acc[ai][bj][m][n]); __builtin_amdgcn_s_setprio(0); } while (0)
; #define PG8_WAIT_V(n) asm volatile("s_waitcnt vmcnt(" #n ")" ::: "memory")
; #define PG8_WAIT_L(n) asm volatile("s_waitcnt lgkmcnt(" #n ")" ::: "memory")
; #define PG8_BAR __builtin_amdgcn_s_barrier()
; #define PG8_SCHED __builtin_amdgcn_sched_barrier(0)
; template <class Epi, class Sched, bool ALIGN_EPI = false, bool SP2 = false, bool F16 = false>
; __device__ __forceinline__ void gemm_phase(PG8_LAS unsigned char* lds, const Gemm g, const Sched& S, const Epi& E) {
;     ...
;             PG8_LDB(B0, 0, 0); PG8_LDB(B1, 0, 1); PG8_SCHED; PG8_LDA(At, 0, 0); PG8_STAGE(PG8_SA(1, 1), a1 + hstep, voffA);
;             PG8_WAIT_V(8); PG8_WAIT_L(0); PG8_BAR; PG8_MMA(0, 0, At, B0); PG8_MMA(0, 1, At, B1); PG8_BAR; PG8_SCHED;
;             PG8_LDA(At, 0, 1); PG8_STAGE(PG8_SB(0, 0), b2, voffB); PG8_STAGE(PG8_SB(0, 1), b2 + hstep, voffB); PG8_STAGE(PG8_SA(0, 0), a2, voffA);
;             PG8_WAIT_V(8); PG8_WAIT_L(0); PG8_BAR; PG8_MMA(1, 0, At, B0); PG8_MMA(1, 1, At, B1); PG8_BAR; PG8_SCHED;
.LBB0_504:
	ds_read_b128 v[36:39], v208
	ds_read_b128 v[48:51], v208 offset:1024
	ds_read_b128 v[136:139], v208 offset:2048
	ds_read_b128 v[140:143], v208 offset:3072
	ds_read_b128 v[144:147], v209
	ds_read_b128 v[148:151], v209 offset:1024
	ds_read_b128 v[152:155], v209 offset:2048
	ds_read_b128 v[156:159], v209 offset:3072
	s_add_u32 s34, s30, 0xfffc0080
	s_addc_u32 s35, s31, -1
	s_cmp_eq_u32 s74, 12
	s_cselect_b32 s37, s23, s35
	s_cselect_b32 s36, s70, s34
	s_cselect_b32 s35, s21, s73
	s_cselect_b32 s34, s71, s72
	v_lshl_add_u64 v[220:221], s[30:31], 0, v[170:171]
	s_add_i32 m0, s41, 0xc000
	ds_read_b128 v[178:181], v210
	ds_read_b128 v[182:185], v210 offset:1024
	ds_read_b128 v[186:189], v210 offset:2048
	ds_read_b128 v[190:193], v210 offset:3072
	ds_read_b128 v[194:197], v210 offset:4096
	ds_read_b128 v[198:201], v210 offset:5120
	ds_read_b128 v[212:215], v210 offset:6144
	ds_read_b128 v[216:219], v210 offset:7168
	global_load_lds_dwordx4 v[220:221], off
	v_lshl_add_u64 v[220:221], s[30:31], 0, v[172:173]
	s_add_i32 m0, s41, 0xe000
	s_nop 0
	global_load_lds_dwordx4 v[220:221], off
	s_waitcnt vmcnt(8)
	s_waitcnt lgkmcnt(0)
	s_barrier
	s_waitcnt lgkmcnt(0)
	v_mfma_f32_16x16x32_bf16 v[132:135], v[36:39], v[178:181], v[132:135]
	v_mfma_f32_16x16x32_bf16 v[124:127], v[136:139], v[178:181], v[124:127]
	v_mfma_f32_16x16x32_bf16 v[116:119], v[36:39], v[186:189], v[116:119]
	v_mfma_f32_16x16x32_bf16 v[108:111], v[136:139], v[186:189], v[108:111]
	v_mfma_f32_16x16x32_bf16 v[100:103], v[36:39], v[194:197], v[100:103]
	v_mfma_f32_16x16x32_bf16 v[92:95], v[136:139], v[194:197], v[92:95]
	v_mfma_f32_16x16x32_bf16 v[84:87], v[36:39], v[212:215], v[84:87]
	v_mfma_f32_16x16x32_bf16 v[76:79], v[136:139], v[212:215], v[76:79]
	v_mfma_f32_16x16x32_bf16 v[132:135], v[48:51], v[182:185], v[132:135]
	v_mfma_f32_16x16x32_bf16 v[124:127], v[140:143], v[182:185], v[124:127]
	v_mfma_f32_16x16x32_bf16 v[116:119], v[48:51], v[190:193], v[116:119]
	v_mfma_f32_16x16x32_bf16 v[108:111], v[140:143], v[190:193], v[108:111]
	v_mfma_f32_16x16x32_bf16 v[100:103], v[48:51], v[198:201], v[100:103]
	v_mfma_f32_16x16x32_bf16 v[92:95], v[140:143], v[198:201], v[92:95]
	v_mfma_f32_16x16x32_bf16 v[84:87], v[48:51], v[216:219], v[84:87]
	v_mfma_f32_16x16x32_bf16 v[76:79], v[140:143], v[216:219], v[76:79]
	v_mfma_f32_16x16x32_bf16 v[128:131], v[144:147], v[178:181], v[128:131]
	v_mfma_f32_16x16x32_bf16 v[120:123], v[152:155], v[178:181], v[120:123]
	v_mfma_f32_16x16x32_bf16 v[112:115], v[144:147], v[186:189], v[112:115]
	v_mfma_f32_16x16x32_bf16 v[104:107], v[152:155], v[186:189], v[104:107]
	v_mfma_f32_16x16x32_bf16 v[96:99], v[144:147], v[194:197], v[96:99]
	v_mfma_f32_16x16x32_bf16 v[88:91], v[152:155], v[194:197], v[88:91]
	v_mfma_f32_16x16x32_bf16 v[80:83], v[144:147], v[212:215], v[80:83]
	v_mfma_f32_16x16x32_bf16 v[72:75], v[152:155], v[212:215], v[72:75]
	v_mfma_f32_16x16x32_bf16 v[128:131], v[148:151], v[182:185], v[128:131]
	v_mfma_f32_16x16x32_bf16 v[120:123], v[156:159], v[182:185], v[120:123]
	v_mfma_f32_16x16x32_bf16 v[112:115], v[148:151], v[190:193], v[112:115]
	v_mfma_f32_16x16x32_bf16 v[104:107], v[156:159], v[190:193], v[104:107]
	v_mfma_f32_16x16x32_bf16 v[96:99], v[148:151], v[198:201], v[96:99]
	v_mfma_f32_16x16x32_bf16 v[88:91], v[156:159], v[198:201], v[88:91]
	v_mfma_f32_16x16x32_bf16 v[80:83], v[148:151], v[216:219], v[80:83]
	v_mfma_f32_16x16x32_bf16 v[72:75], v[156:159], v[216:219], v[72:75]
	s_barrier
	s_add_i32 s75, s68, s40
	v_lshl_add_u64 v[220:221], s[34:35], 0, v[164:165]
	s_mov_b32 m0, s75
	ds_read_b128 v[178:181], v210 offset:16384
	ds_read_b128 v[182:185], v210 offset:17408
	ds_read_b128 v[186:189], v210 offset:18432
	ds_read_b128 v[190:193], v210 offset:19456
	ds_read_b128 v[194:197], v210 offset:20480
	ds_read_b128 v[198:201], v210 offset:21504
	ds_read_b128 v[212:215], v210 offset:22528
	ds_read_b128 v[216:219], v210 offset:23552
	global_load_lds_dwordx4 v[220:221], off
	s_add_i32 m0, s75, 0x2000
	s_add_u32 s76, s34, 0x40000
	v_lshl_add_u64 v[222:223], s[34:35], 0, v[168:169]
	s_addc_u32 s77, s35, 0
	s_add_i32 s75, s69, s40
	global_load_lds_dwordx4 v[222:223], off
	v_lshl_add_u64 v[240:241], s[76:77], 0, v[164:165]
	s_mov_b32 m0, s75
	v_lshl_add_u64 v[242:243], s[36:37], 0, v[166:167]
	global_load_lds_dwordx4 v[240:241], off
	v_lshl_add_u64 v[240:241], s[76:77], 0, v[168:169]
	s_add_i32 m0, s75, 0x2000
	s_nop 0
	global_load_lds_dwordx4 v[240:241], off
	v_lshl_add_u64 v[240:241], s[36:37], 0, v[162:163]
	s_mov_b32 m0, s41
	s_nop 0
	global_load_lds_dwordx4 v[240:241], off
	s_mov_b32 m0, s42
	s_nop 0
	global_load_lds_dwordx4 v[242:243], off
	s_waitcnt vmcnt(8)
	s_waitcnt lgkmcnt(0)
	s_barrier
; #define PG8_STAGE(bufoff, gbase, voff) do { _Pragma("unroll") for (int _i = 0; _i < 2; ++_i) \
;         __builtin_amdgcn_global_load_lds((const unsigned*)((const char*)(gbase) + (voff)[_i]), (PG8_LAS unsigned*)(lds + (bufoff) + ldsw + _i * 8192), 16, 0, 0); } while (0)
; #define PG8_LDA(dst, b, h) do { _Pragma("unroll") for (int m = 0; m < 4; ++m) _Pragma("unroll") for (int k = 0; k < 2; ++k) dst[m][k] = *(const PG8_LAS bf16x8*)(lds + PG8_SA(b, h) + aoff + m * 2048 + k * 1024); } while (0)
; #define PG8_LDB(dst, b, h) do { _Pragma("unroll") for (int n = 0; n < 2; ++n) _Pragma("unroll") for (int k = 0; k < 2; ++k) dst[n][k] = *(const PG8_LAS bf16x8*)(lds + PG8_SB(b, h) + boff + n * 2048 + k * 1024); } while (0)
; #define PG8_MMA(ai, bj, At, Bt) do { __builtin_amdgcn_s_setprio(1); _Pragma("unroll") for (int m = 0; m < 4; ++m) _Pragma("unroll") for (int n = 0; n < 2; ++n) _Pragma("unroll") for (int k = 0; k < 2; ++k) \
;         acc[ai][bj][m][n] = mma16<F16>(Bt[n][k], At[m][k], acc[ai][bj][m][n]); __builtin_amdgcn_s_setprio(0); } while (0)
; #define PG8_WAIT_V(n) asm volatile("s_waitcnt vmcnt(" #n ")" ::: "memory")
; #define PG8_WAIT_L(n) asm volatile("s_waitcnt lgkmcnt(" #n ")" ::: "memory")
; #define PG8_BAR __builtin_amdgcn_s_barrier()
; #define PG8_SCHED __builtin_amdgcn_sched_barrier(0)
; template <class Epi, class Sched, bool ALIGN_EPI = false, bool SP2 = false, bool F16 = false>
; __device__ __forceinline__ void gemm_phase(PG8_LAS unsigned char* lds, const Gemm g, const Sched& S, const Epi& E) {
;     ...
;             PG8_WAIT_V(8); PG8_WAIT_L(0); PG8_BAR; PG8_MMA(1, 0, At, B0); PG8_MMA(1, 1, At, B1); PG8_BAR; PG8_SCHED;
;             PG8_LDB(B0, 1, 0); PG8_LDB(B1, 1, 1); PG8_SCHED; PG8_LDA(At, 1, 0); PG8_STAGE(PG8_SA(0, 1), a2 + hstep, voffA);
;             PG8_WAIT_V(8); PG8_WAIT_L(0); PG8_BAR; PG8_MMA(0, 0, At, B0); PG8_MMA(0, 1, At, B1); PG8_BAR; PG8_SCHED;
	s_waitcnt lgkmcnt(0)
	v_mfma_f32_16x16x32_bf16 v[68:71], v[36:39], v[178:181], v[68:71]
	v_mfma_f32_16x16x32_bf16 v[60:63], v[136:139], v[178:181], v[60:63]
	v_mfma_f32_16x16x32_bf16 v[52:55], v[36:39], v[186:189], v[52:55]
	v_mfma_f32_16x16x32_bf16 v[40:43], v[136:139], v[186:189], v[40:43]
	v_mfma_f32_16x16x32_bf16 v[28:31], v[36:39], v[194:197], v[28:31]
	v_mfma_f32_16x16x32_bf16 v[20:23], v[136:139], v[194:197], v[20:23]
	v_mfma_f32_16x16x32_bf16 v[12:15], v[36:39], v[212:215], v[12:15]
	v_mfma_f32_16x16x32_bf16 v[4:7], v[136:139], v[212:215], v[4:7]
	v_mfma_f32_16x16x32_bf16 v[68:71], v[48:51], v[182:185], v[68:71]
	v_mfma_f32_16x16x32_bf16 v[60:63], v[140:143], v[182:185], v[60:63]
	v_mfma_f32_16x16x32_bf16 v[52:55], v[48:51], v[190:193], v[52:55]
	v_mfma_f32_16x16x32_bf16 v[40:43], v[140:143], v[190:193], v[40:43]
	v_mfma_f32_16x16x32_bf16 v[28:31], v[48:51], v[198:201], v[28:31]
	v_mfma_f32_16x16x32_bf16 v[20:23], v[140:143], v[198:201], v[20:23]
	v_mfma_f32_16x16x32_bf16 v[12:15], v[48:51], v[216:219], v[12:15]
	v_mfma_f32_16x16x32_bf16 v[4:7], v[140:143], v[216:219], v[4:7]
	v_mfma_f32_16x16x32_bf16 v[44:47], v[144:147], v[186:189], v[44:47]
	v_mfma_f32_16x16x32_bf16 v[32:35], v[152:155], v[186:189], v[32:35]
	v_mfma_f32_16x16x32_bf16 v[24:27], v[144:147], v[194:197], v[24:27]
	v_mfma_f32_16x16x32_bf16 v[16:19], v[152:155], v[194:197], v[16:19]
	v_mfma_f32_16x16x32_bf16 v[8:11], v[144:147], v[212:215], v[8:11]
	v_mfma_f32_16x16x32_bf16 v[0:3], v[152:155], v[212:215], v[0:3]
	v_mfma_f32_16x16x32_bf16 v[36:39], v[144:147], v[178:181], v[64:67]
	v_mfma_f32_16x16x32_bf16 v[48:51], v[152:155], v[178:181], v[56:59]
	v_mfma_f32_16x16x32_bf16 v[44:47], v[148:151], v[190:193], v[44:47]
	v_mfma_f32_16x16x32_bf16 v[32:35], v[156:159], v[190:193], v[32:35]
	v_mfma_f32_16x16x32_bf16 v[24:27], v[148:151], v[198:201], v[24:27]
	v_mfma_f32_16x16x32_bf16 v[16:19], v[156:159], v[198:201], v[16:19]
	v_mfma_f32_16x16x32_bf16 v[8:11], v[148:151], v[216:219], v[8:11]
	v_mfma_f32_16x16x32_bf16 v[0:3], v[156:159], v[216:219], v[0:3]
	v_mfma_f32_16x16x32_bf16 v[36:39], v[148:151], v[182:185], v[36:39]
	v_mfma_f32_16x16x32_bf16 v[48:51], v[156:159], v[182:185], v[48:51]
	s_barrier
	s_add_i32 s75, 0, 0x18000
	s_add_i32 s76, 0, 0x1c000
	v_add_u32_e32 v140, s75, v206
	v_add_u32_e32 v156, s76, v206
	ds_read_b128 v[56:59], v140
	ds_read_b128 v[64:67], v140 offset:1024
	ds_read_b128 v[136:139], v140 offset:2048
	ds_read_b128 v[140:143], v140 offset:3072
	ds_read_b128 v[144:147], v156
	ds_read_b128 v[148:151], v156 offset:1024
	ds_read_b128 v[152:155], v156 offset:2048
	ds_read_b128 v[156:159], v156 offset:3072
	s_add_u32 s36, s36, 0x40000
	s_addc_u32 s37, s37, 0
	s_mov_b32 m0, s43
	v_lshl_add_u64 v[244:245], s[36:37], 0, v[162:163]
	ds_read_b128 v[178:181], v210 offset:32768
	ds_read_b128 v[182:185], v210 offset:33792
	ds_read_b128 v[186:189], v210 offset:34816
	ds_read_b128 v[190:193], v210 offset:35840
	ds_read_b128 v[194:197], v210 offset:36864
	ds_read_b128 v[198:201], v210 offset:37888
	ds_read_b128 v[212:215], v210 offset:38912
	ds_read_b128 v[216:219], v210 offset:39936
	global_load_lds_dwordx4 v[244:245], off
	v_lshl_add_u64 v[244:245], s[36:37], 0, v[166:167]
	s_mov_b32 m0, s62
	s_nop 0
	global_load_lds_dwordx4 v[244:245], off
	s_waitcnt vmcnt(8)
	s_waitcnt lgkmcnt(0)
	s_barrier
	s_waitcnt lgkmcnt(0)
	v_mfma_f32_16x16x32_bf16 v[132:135], v[56:59], v[178:181], v[132:135]
	v_mfma_f32_16x16x32_bf16 v[124:127], v[136:139], v[178:181], v[124:127]
	v_mfma_f32_16x16x32_bf16 v[116:119], v[56:59], v[186:189], v[116:119]
	v_mfma_f32_16x16x32_bf16 v[108:111], v[136:139], v[186:189], v[108:111]
	v_mfma_f32_16x16x32_bf16 v[100:103], v[56:59], v[194:197], v[100:103]
	v_mfma_f32_16x16x32_bf16 v[92:95], v[136:139], v[194:197], v[92:95]
	v_mfma_f32_16x16x32_bf16 v[84:87], v[56:59], v[212:215], v[84:87]
	v_mfma_f32_16x16x32_bf16 v[76:79], v[136:139], v[212:215], v[76:79]
	v_mfma_f32_16x16x32_bf16 v[132:135], v[64:67], v[182:185], v[132:135]
	v_mfma_f32_16x16x32_bf16 v[124:127], v[140:143], v[182:185], v[124:127]
	v_mfma_f32_16x16x32_bf16 v[116:119], v[64:67], v[190:193], v[116:119]
	v_mfma_f32_16x16x32_bf16 v[108:111], v[140:143], v[190:193], v[108:111]
	v_mfma_f32_16x16x32_bf16 v[100:103], v[64:67], v[198:201], v[100:103]
	v_mfma_f32_16x16x32_bf16 v[92:95], v[140:143], v[198:201], v[92:95]
	v_mfma_f32_16x16x32_bf16 v[84:87], v[64:67], v[216:219], v[84:87]
	v_mfma_f32_16x16x32_bf16 v[76:79], v[140:143], v[216:219], v[76:79]
	v_mfma_f32_16x16x32_bf16 v[128:131], v[144:147], v[178:181], v[128:131]
	v_mfma_f32_16x16x32_bf16 v[120:123], v[152:155], v[178:181], v[120:123]
	v_mfma_f32_16x16x32_bf16 v[112:115], v[144:147], v[186:189], v[112:115]
	v_mfma_f32_16x16x32_bf16 v[104:107], v[152:155], v[186:189], v[104:107]
	v_mfma_f32_16x16x32_bf16 v[96:99], v[144:147], v[194:197], v[96:99]
	v_mfma_f32_16x16x32_bf16 v[88:91], v[152:155], v[194:197], v[88:91]
	v_mfma_f32_16x16x32_bf16 v[80:83], v[144:147], v[212:215], v[80:83]
	v_mfma_f32_16x16x32_bf16 v[72:75], v[152:155], v[212:215], v[72:75]
	v_mfma_f32_16x16x32_bf16 v[128:131], v[148:151], v[182:185], v[128:131]
	v_mfma_f32_16x16x32_bf16 v[120:123], v[156:159], v[182:185], v[120:123]
	v_mfma_f32_16x16x32_bf16 v[112:115], v[148:151], v[190:193], v[112:115]
	v_mfma_f32_16x16x32_bf16 v[104:107], v[156:159], v[190:193], v[104:107]
	v_mfma_f32_16x16x32_bf16 v[96:99], v[148:151], v[198:201], v[96:99]
	v_mfma_f32_16x16x32_bf16 v[88:91], v[156:159], v[198:201], v[88:91]
	v_mfma_f32_16x16x32_bf16 v[80:83], v[148:151], v[216:219], v[80:83]
	v_mfma_f32_16x16x32_bf16 v[72:75], v[156:159], v[216:219], v[72:75]
	s_barrier
; #define PG8_STAGE(bufoff, gbase, voff) do { _Pragma("unroll") for (int _i = 0; _i < 2; ++_i) \
;         __builtin_amdgcn_global_load_lds((const unsigned*)((const char*)(gbase) + (voff)[_i]), (PG8_LAS unsigned*)(lds + (bufoff) + ldsw + _i * 8192), 16, 0, 0); } while (0)
; #define PG8_LDA(dst, b, h) do { _Pragma("unroll") for (int m = 0; m < 4; ++m) _Pragma("unroll") for (int k = 0; k < 2; ++k) dst[m][k] = *(const PG8_LAS bf16x8*)(lds + PG8_SA(b, h) + aoff + m * 2048 + k * 1024); } while (0)
; #define PG8_MMA(ai, bj, At, Bt) do { __builtin_amdgcn_s_setprio(1); _Pragma("unroll") for (int m = 0; m < 4; ++m) _Pragma("unroll") for (int n = 0; n < 2; ++n) _Pragma("unroll") for (int k = 0; k < 2; ++k) \
;         acc[ai][bj][m][n] = mma16<F16>(Bt[n][k], At[m][k], acc[ai][bj][m][n]); __builtin_amdgcn_s_setprio(0); } while (0)
; #define PG8_WAIT_V(n) asm volatile("s_waitcnt vmcnt(" #n ")" ::: "memory")
; #define PG8_WAIT_L(n) asm volatile("s_waitcnt lgkmcnt(" #n ")" ::: "memory")
; #define PG8_BAR __builtin_amdgcn_s_barrier()
; #define PG8_SCHED __builtin_amdgcn_sched_barrier(0)
; template <class Epi, class Sched, bool ALIGN_EPI = false, bool SP2 = false, bool F16 = false>
; __device__ __forceinline__ void gemm_phase(PG8_LAS unsigned char* lds, const Gemm g, const Sched& S, const Epi& E) {
;     ...
;             PG8_LDA(At, 1, 1); PG8_STAGE(PG8_SB(1, 0), b3, voffB); PG8_STAGE(PG8_SB(1, 1), b3 + hstep, voffB); PG8_STAGE(PG8_SA(1, 0), a3, voffA);
;             PG8_WAIT_V(8); PG8_WAIT_L(0); PG8_BAR; PG8_MMA(1, 0, At, B0); PG8_MMA(1, 1, At, B1); PG8_BAR; PG8_SCHED;
	s_add_i32 s36, s75, s40
	v_lshl_add_u64 v[220:221], v[220:221], 0, s[6:7]
	s_mov_b32 m0, s36
	ds_read_b128 v[178:181], v210 offset:49152
	ds_read_b128 v[182:185], v210 offset:50176
	ds_read_b128 v[186:189], v210 offset:51200
	ds_read_b128 v[190:193], v210 offset:52224
	ds_read_b128 v[194:197], v210 offset:53248
	ds_read_b128 v[198:201], v210 offset:54272
	ds_read_b128 v[212:215], v210 offset:55296
	ds_read_b128 v[216:219], v210 offset:56320
	global_load_lds_dwordx4 v[220:221], off
	s_add_i32 m0, s36, 0x2000
	s_add_u32 s34, s34, 0x40080
	v_lshl_add_u64 v[220:221], v[222:223], 0, s[6:7]
	s_addc_u32 s35, s35, 0
	s_add_i32 s36, s76, s40
	global_load_lds_dwordx4 v[220:221], off
	v_lshl_add_u64 v[220:221], s[34:35], 0, v[164:165]
	s_mov_b32 m0, s36
	s_nop 0
	global_load_lds_dwordx4 v[220:221], off
	v_lshl_add_u64 v[220:221], s[34:35], 0, v[168:169]
	s_add_i32 m0, s36, 0x2000
	s_nop 0
	global_load_lds_dwordx4 v[220:221], off
	v_lshl_add_u64 v[220:221], v[240:241], 0, s[6:7]
	s_mov_b32 m0, s64
	s_nop 0
	global_load_lds_dwordx4 v[220:221], off
	v_lshl_add_u64 v[220:221], v[242:243], 0, s[6:7]
	s_mov_b32 m0, s65
	s_nop 0
	global_load_lds_dwordx4 v[220:221], off
	s_waitcnt vmcnt(8)
	s_waitcnt lgkmcnt(0)
	s_barrier
	s_waitcnt lgkmcnt(0)
	v_mfma_f32_16x16x32_bf16 v[68:71], v[56:59], v[178:181], v[68:71]
	v_mfma_f32_16x16x32_bf16 v[60:63], v[136:139], v[178:181], v[60:63]
	v_mfma_f32_16x16x32_bf16 v[52:55], v[56:59], v[186:189], v[52:55]
	v_mfma_f32_16x16x32_bf16 v[40:43], v[136:139], v[186:189], v[40:43]
	v_mfma_f32_16x16x32_bf16 v[28:31], v[56:59], v[194:197], v[28:31]
	v_mfma_f32_16x16x32_bf16 v[20:23], v[136:139], v[194:197], v[20:23]
	v_mfma_f32_16x16x32_bf16 v[12:15], v[56:59], v[212:215], v[12:15]
	v_mfma_f32_16x16x32_bf16 v[4:7], v[136:139], v[212:215], v[4:7]
	v_mfma_f32_16x16x32_bf16 v[68:71], v[64:67], v[182:185], v[68:71]
	v_mfma_f32_16x16x32_bf16 v[60:63], v[140:143], v[182:185], v[60:63]
	v_mfma_f32_16x16x32_bf16 v[52:55], v[64:67], v[190:193], v[52:55]
	v_mfma_f32_16x16x32_bf16 v[40:43], v[140:143], v[190:193], v[40:43]
	v_mfma_f32_16x16x32_bf16 v[28:31], v[64:67], v[198:201], v[28:31]
	v_mfma_f32_16x16x32_bf16 v[20:23], v[140:143], v[198:201], v[20:23]
	v_mfma_f32_16x16x32_bf16 v[12:15], v[64:67], v[216:219], v[12:15]
	v_mfma_f32_16x16x32_bf16 v[4:7], v[140:143], v[216:219], v[4:7]
	v_mfma_f32_16x16x32_bf16 v[36:39], v[144:147], v[178:181], v[36:39]
	v_mfma_f32_16x16x32_bf16 v[64:67], v[148:151], v[182:185], v[36:39]
	v_mfma_f32_16x16x32_bf16 v[36:39], v[152:155], v[178:181], v[48:51]
	v_mfma_f32_16x16x32_bf16 v[56:59], v[156:159], v[182:185], v[36:39]
	v_mfma_f32_16x16x32_bf16 v[36:39], v[144:147], v[186:189], v[44:47]
	v_mfma_f32_16x16x32_bf16 v[32:35], v[152:155], v[186:189], v[32:35]
	v_mfma_f32_16x16x32_bf16 v[24:27], v[144:147], v[194:197], v[24:27]
	v_mfma_f32_16x16x32_bf16 v[16:19], v[152:155], v[194:197], v[16:19]
	v_mfma_f32_16x16x32_bf16 v[8:11], v[144:147], v[212:215], v[8:11]
	v_mfma_f32_16x16x32_bf16 v[0:3], v[152:155], v[212:215], v[0:3]
	v_mfma_f32_16x16x32_bf16 v[44:47], v[148:151], v[190:193], v[36:39]
	v_mfma_f32_16x16x32_bf16 v[32:35], v[156:159], v[190:193], v[32:35]
	v_mfma_f32_16x16x32_bf16 v[24:27], v[148:151], v[198:201], v[24:27]
	v_mfma_f32_16x16x32_bf16 v[16:19], v[156:159], v[198:201], v[16:19]
	v_mfma_f32_16x16x32_bf16 v[8:11], v[148:151], v[216:219], v[8:11]
	v_mfma_f32_16x16x32_bf16 v[0:3], v[156:159], v[216:219], v[0:3]
	s_barrier
	s_add_i32 s74, s74, 2
	s_add_u32 s30, s30, 0x100
	s_addc_u32 s31, s31, 0
	s_add_u32 s72, s72, 0x100
	s_addc_u32 s73, s73, 0
	s_cmp_gt_u32 s74, 13
	s_cbranch_scc0 .LBB0_504
	s_and_b64 vcc, exec, s[12:13]
	s_cbranch_vccz .LBB0_507
	s_barrier

; #define PG8_STAGE(bufoff, gbase, voff) do { _Pragma("unroll") for (int _i = 0; _i < 2; ++_i) \
;         __builtin_amdgcn_global_load_lds((const unsigned*)((const char*)(gbase) + (voff)[_i]), (PG8_LAS unsigned*)(lds + (bufoff) + ldsw + _i * 8192), 16, 0, 0); } while (0)
; #define PG8_LDA(dst, b, h) do { _Pragma("unroll") for (int m = 0; m < 4; ++m) _Pragma("unroll") for (int k = 0; k < 2; ++k) dst[m][k] = *(const PG8_LAS bf16x8*)(lds + PG8_SA(b, h) + aoff + m * 2048 + k * 1024); } while (0)
; #define PG8_LDB(dst, b, h) do { _Pragma("unroll") for (int n = 0; n < 2; ++n) _Pragma("unroll") for (int k = 0; k < 2; ++k) dst[n][k] = *(const PG8_LAS bf16x8*)(lds + PG8_SB(b, h) + boff + n * 2048 + k * 1024); } while (0)
; #define PG8_MMA(ai, bj, At, Bt) do { __builtin_amdgcn_s_setprio(1); _Pragma("unroll") for (int m = 0; m < 4; ++m) _Pragma("unroll") for (int n = 0; n < 2; ++n) _Pragma("unroll") for (int k = 0; k < 2; ++k) \
;         acc[ai][bj][m][n] = mma16<F16>(Bt[n][k], At[m][k], acc[ai][bj][m][n]); __builtin_amdgcn_s_setprio(0); } while (0)
; #define PG8_WAIT_V(n) asm volatile("s_waitcnt vmcnt(" #n ")" ::: "memory")
; #define PG8_WAIT_L(n) asm volatile("s_waitcnt lgkmcnt(" #n ")" ::: "memory")
; #define PG8_BAR __builtin_amdgcn_s_barrier()
; #define PG8_SCHED __builtin_amdgcn_sched_barrier(0)
; template <class Epi, class Sched, bool ALIGN_EPI = false, bool SP2 = false, bool F16 = false>
; __device__ __forceinline__ void gemm_phase(PG8_LAS unsigned char* lds, const Gemm g, const Sched& S, const Epi& E) {
;     ...
;             PG8_LDB(B0, 0, 0); PG8_LDB(B1, 0, 1); PG8_SCHED; PG8_LDA(At, 0, 0); PG8_STAGE(PG8_SA(1, 1), a1 + hstep, voffA);
;             PG8_WAIT_V(8); PG8_WAIT_L(0); PG8_BAR; PG8_MMA(0, 0, At, B0); PG8_MMA(0, 1, At, B1); PG8_BAR; PG8_SCHED;
;             PG8_LDA(At, 0, 1); PG8_STAGE(PG8_SB(0, 0), b2, voffB); PG8_STAGE(PG8_SB(0, 1), b2 + hstep, voffB); PG8_STAGE(PG8_SA(0, 0), a2, voffA);
;             PG8_WAIT_V(8); PG8_WAIT_L(0); PG8_BAR; PG8_MMA(1, 0, At, B0); PG8_MMA(1, 1, At, B1); PG8_BAR; PG8_SCHED;
.LBB0_582:
	ds_read_b128 v[128:131], v190
	ds_read_b128 v[132:135], v190 offset:1024
	ds_read_b128 v[136:139], v190 offset:2048
	ds_read_b128 v[140:143], v190 offset:3072
	ds_read_b128 v[144:147], v191
	ds_read_b128 v[148:151], v191 offset:1024
	ds_read_b128 v[170:173], v191 offset:2048
	ds_read_b128 v[174:177], v191 offset:3072
	s_add_u32 s34, s30, 0xfffc0080
	s_addc_u32 s35, s31, -1
	s_cmp_eq_u32 s62, 12
	s_cselect_b32 s37, s21, s35
	s_cselect_b32 s36, s27, s34
	s_cselect_b32 s35, s19, s61
	s_cselect_b32 s34, s55, s60
	v_lshl_add_u64 v[186:187], s[30:31], 0, v[152:153]
	s_add_i32 m0, s29, 0xc000
	ds_read_b128 v[178:181], v192
	ds_read_b128 v[182:185], v192 offset:1024
	ds_read_b128 v[194:197], v192 offset:2048
	ds_read_b128 v[198:201], v192 offset:3072
	ds_read_b128 v[202:205], v192 offset:4096
	ds_read_b128 v[206:209], v192 offset:5120
	ds_read_b128 v[210:213], v192 offset:6144
	ds_read_b128 v[214:217], v192 offset:7168
	global_load_lds_dwordx4 v[186:187], off
	v_lshl_add_u64 v[186:187], s[30:31], 0, v[154:155]
	s_add_i32 m0, s29, 0xe000
	s_nop 0
	global_load_lds_dwordx4 v[186:187], off
	s_waitcnt vmcnt(8)
	s_waitcnt lgkmcnt(0)
	s_barrier
	s_waitcnt lgkmcnt(0)
	v_mfma_f32_16x16x32_bf16 v[124:127], v[128:131], v[178:181], v[124:127]
	v_mfma_f32_16x16x32_bf16 v[120:123], v[136:139], v[178:181], v[120:123]
	v_mfma_f32_16x16x32_bf16 v[108:111], v[128:131], v[194:197], v[108:111]
	v_mfma_f32_16x16x32_bf16 v[104:107], v[136:139], v[194:197], v[104:107]
	v_mfma_f32_16x16x32_bf16 v[92:95], v[128:131], v[202:205], v[92:95]
	v_mfma_f32_16x16x32_bf16 v[88:91], v[136:139], v[202:205], v[88:91]
	v_mfma_f32_16x16x32_bf16 v[76:79], v[128:131], v[210:213], v[76:79]
	v_mfma_f32_16x16x32_bf16 v[72:75], v[136:139], v[210:213], v[72:75]
	v_mfma_f32_16x16x32_bf16 v[124:127], v[132:135], v[182:185], v[124:127]
	v_mfma_f32_16x16x32_bf16 v[120:123], v[140:143], v[182:185], v[120:123]
	v_mfma_f32_16x16x32_bf16 v[108:111], v[132:135], v[198:201], v[108:111]
	v_mfma_f32_16x16x32_bf16 v[104:107], v[140:143], v[198:201], v[104:107]
	v_mfma_f32_16x16x32_bf16 v[92:95], v[132:135], v[206:209], v[92:95]
	v_mfma_f32_16x16x32_bf16 v[88:91], v[140:143], v[206:209], v[88:91]
	v_mfma_f32_16x16x32_bf16 v[76:79], v[132:135], v[214:217], v[76:79]
	v_mfma_f32_16x16x32_bf16 v[72:75], v[140:143], v[214:217], v[72:75]
	v_mfma_f32_16x16x32_bf16 v[116:119], v[144:147], v[178:181], v[116:119]
	v_mfma_f32_16x16x32_bf16 v[112:115], v[170:173], v[178:181], v[112:115]
	v_mfma_f32_16x16x32_bf16 v[100:103], v[144:147], v[194:197], v[100:103]
	v_mfma_f32_16x16x32_bf16 v[96:99], v[170:173], v[194:197], v[96:99]
	v_mfma_f32_16x16x32_bf16 v[84:87], v[144:147], v[202:205], v[84:87]
	v_mfma_f32_16x16x32_bf16 v[80:83], v[170:173], v[202:205], v[80:83]
	v_mfma_f32_16x16x32_bf16 v[68:71], v[144:147], v[210:213], v[68:71]
	v_mfma_f32_16x16x32_bf16 v[64:67], v[170:173], v[210:213], v[64:67]
	v_mfma_f32_16x16x32_bf16 v[116:119], v[148:151], v[182:185], v[116:119]
	v_mfma_f32_16x16x32_bf16 v[112:115], v[174:177], v[182:185], v[112:115]
	v_mfma_f32_16x16x32_bf16 v[100:103], v[148:151], v[198:201], v[100:103]
	v_mfma_f32_16x16x32_bf16 v[96:99], v[174:177], v[198:201], v[96:99]
	v_mfma_f32_16x16x32_bf16 v[84:87], v[148:151], v[206:209], v[84:87]
	v_mfma_f32_16x16x32_bf16 v[80:83], v[174:177], v[206:209], v[80:83]
	v_mfma_f32_16x16x32_bf16 v[68:71], v[148:151], v[214:217], v[68:71]
	v_mfma_f32_16x16x32_bf16 v[64:67], v[174:177], v[214:217], v[64:67]
	s_barrier
	s_add_i32 s63, s53, s39
	v_lshl_add_u64 v[186:187], s[34:35], 0, v[164:165]
	s_mov_b32 m0, s63
	ds_read_b128 v[178:181], v192 offset:16384
	ds_read_b128 v[182:185], v192 offset:17408
	ds_read_b128 v[194:197], v192 offset:18432
	ds_read_b128 v[198:201], v192 offset:19456
	ds_read_b128 v[202:205], v192 offset:20480
	ds_read_b128 v[206:209], v192 offset:21504
	ds_read_b128 v[210:213], v192 offset:22528
	ds_read_b128 v[214:217], v192 offset:23552
	global_load_lds_dwordx4 v[186:187], off
	s_add_i32 m0, s63, 0x2000
	s_add_u32 s64, s34, 0x40000
	v_lshl_add_u64 v[218:219], s[34:35], 0, v[168:169]
	s_addc_u32 s65, s35, 0
	s_add_i32 s63, s54, s39
	global_load_lds_dwordx4 v[218:219], off
	v_lshl_add_u64 v[220:221], s[64:65], 0, v[164:165]
	s_mov_b32 m0, s63
	v_lshl_add_u64 v[222:223], s[36:37], 0, v[166:167]
	global_load_lds_dwordx4 v[220:221], off
	v_lshl_add_u64 v[220:221], s[64:65], 0, v[168:169]
	s_add_i32 m0, s63, 0x2000
	s_nop 0
	global_load_lds_dwordx4 v[220:221], off
	v_lshl_add_u64 v[220:221], s[36:37], 0, v[162:163]
	s_mov_b32 m0, s29
	s_nop 0
	global_load_lds_dwordx4 v[220:221], off
	s_mov_b32 m0, s40
	s_nop 0
	global_load_lds_dwordx4 v[222:223], off
	s_waitcnt vmcnt(8)
	s_waitcnt lgkmcnt(0)
	s_barrier
; #define PG8_STAGE(bufoff, gbase, voff) do { _Pragma("unroll") for (int _i = 0; _i < 2; ++_i) \
;         __builtin_amdgcn_global_load_lds((const unsigned*)((const char*)(gbase) + (voff)[_i]), (PG8_LAS unsigned*)(lds + (bufoff) + ldsw + _i * 8192), 16, 0, 0); } while (0)
; #define PG8_LDA(dst, b, h) do { _Pragma("unroll") for (int m = 0; m < 4; ++m) _Pragma("unroll") for (int k = 0; k < 2; ++k) dst[m][k] = *(const PG8_LAS bf16x8*)(lds + PG8_SA(b, h) + aoff + m * 2048 + k * 1024); } while (0)
; #define PG8_LDB(dst, b, h) do { _Pragma("unroll") for (int n = 0; n < 2; ++n) _Pragma("unroll") for (int k = 0; k < 2; ++k) dst[n][k] = *(const PG8_LAS bf16x8*)(lds + PG8_SB(b, h) + boff + n * 2048 + k * 1024); } while (0)
; #define PG8_MMA(ai, bj, At, Bt) do { __builtin_amdgcn_s_setprio(1); _Pragma("unroll") for (int m = 0; m < 4; ++m) _Pragma("unroll") for (int n = 0; n < 2; ++n) _Pragma("unroll") for (int k = 0; k < 2; ++k) \
;         acc[ai][bj][m][n] = mma16<F16>(Bt[n][k], At[m][k], acc[ai][bj][m][n]); __builtin_amdgcn_s_setprio(0); } while (0)
; #define PG8_WAIT_V(n) asm volatile("s_waitcnt vmcnt(" #n ")" ::: "memory")
; #define PG8_WAIT_L(n) asm volatile("s_waitcnt lgkmcnt(" #n ")" ::: "memory")
; #define PG8_BAR __builtin_amdgcn_s_barrier()
; #define PG8_SCHED __builtin_amdgcn_sched_barrier(0)
; template <class Epi, class Sched, bool ALIGN_EPI = false, bool SP2 = false, bool F16 = false>
; __device__ __forceinline__ void gemm_phase(PG8_LAS unsigned char* lds, const Gemm g, const Sched& S, const Epi& E) {
;     ...
;             PG8_WAIT_V(8); PG8_WAIT_L(0); PG8_BAR; PG8_MMA(1, 0, At, B0); PG8_MMA(1, 1, At, B1); PG8_BAR; PG8_SCHED;
;             PG8_LDB(B0, 1, 0); PG8_LDB(B1, 1, 1); PG8_SCHED; PG8_LDA(At, 1, 0); PG8_STAGE(PG8_SA(0, 1), a2 + hstep, voffA);
;             PG8_WAIT_V(8); PG8_WAIT_L(0); PG8_BAR; PG8_MMA(0, 0, At, B0); PG8_MMA(0, 1, At, B1); PG8_BAR; PG8_SCHED;
	s_waitcnt lgkmcnt(0)
	v_mfma_f32_16x16x32_bf16 v[60:63], v[128:131], v[178:181], v[60:63]
	v_mfma_f32_16x16x32_bf16 v[56:59], v[136:139], v[178:181], v[56:59]
	v_mfma_f32_16x16x32_bf16 v[44:47], v[128:131], v[194:197], v[44:47]
	v_mfma_f32_16x16x32_bf16 v[40:43], v[136:139], v[194:197], v[40:43]
	v_mfma_f32_16x16x32_bf16 v[28:31], v[128:131], v[202:205], v[28:31]
	v_mfma_f32_16x16x32_bf16 v[24:27], v[136:139], v[202:205], v[24:27]
	v_mfma_f32_16x16x32_bf16 v[12:15], v[128:131], v[210:213], v[12:15]
	v_mfma_f32_16x16x32_bf16 v[8:11], v[136:139], v[210:213], v[8:11]
	v_mfma_f32_16x16x32_bf16 v[60:63], v[132:135], v[182:185], v[60:63]
	v_mfma_f32_16x16x32_bf16 v[56:59], v[140:143], v[182:185], v[56:59]
	v_mfma_f32_16x16x32_bf16 v[44:47], v[132:135], v[198:201], v[44:47]
	v_mfma_f32_16x16x32_bf16 v[40:43], v[140:143], v[198:201], v[40:43]
	v_mfma_f32_16x16x32_bf16 v[28:31], v[132:135], v[206:209], v[28:31]
	v_mfma_f32_16x16x32_bf16 v[24:27], v[140:143], v[206:209], v[24:27]
	v_mfma_f32_16x16x32_bf16 v[12:15], v[132:135], v[214:217], v[12:15]
	v_mfma_f32_16x16x32_bf16 v[8:11], v[140:143], v[214:217], v[8:11]
	v_mfma_f32_16x16x32_bf16 v[52:55], v[144:147], v[178:181], v[52:55]
	v_mfma_f32_16x16x32_bf16 v[48:51], v[170:173], v[178:181], v[48:51]
	v_mfma_f32_16x16x32_bf16 v[36:39], v[144:147], v[194:197], v[36:39]
	v_mfma_f32_16x16x32_bf16 v[32:35], v[170:173], v[194:197], v[32:35]
	v_mfma_f32_16x16x32_bf16 v[20:23], v[144:147], v[202:205], v[20:23]
	v_mfma_f32_16x16x32_bf16 v[16:19], v[170:173], v[202:205], v[16:19]
	v_mfma_f32_16x16x32_bf16 v[4:7], v[144:147], v[210:213], v[4:7]
	v_mfma_f32_16x16x32_bf16 v[0:3], v[170:173], v[210:213], v[0:3]
	v_mfma_f32_16x16x32_bf16 v[52:55], v[148:151], v[182:185], v[52:55]
	v_mfma_f32_16x16x32_bf16 v[48:51], v[174:177], v[182:185], v[48:51]
	v_mfma_f32_16x16x32_bf16 v[36:39], v[148:151], v[198:201], v[36:39]
	v_mfma_f32_16x16x32_bf16 v[32:35], v[174:177], v[198:201], v[32:35]
	v_mfma_f32_16x16x32_bf16 v[20:23], v[148:151], v[206:209], v[20:23]
	v_mfma_f32_16x16x32_bf16 v[16:19], v[174:177], v[206:209], v[16:19]
	v_mfma_f32_16x16x32_bf16 v[4:7], v[148:151], v[214:217], v[4:7]
	v_mfma_f32_16x16x32_bf16 v[0:3], v[174:177], v[214:217], v[0:3]
	s_barrier
	s_add_i32 s63, 0, 0x18000
	s_add_i32 s64, 0, 0x1c000
	v_add_u32_e32 v140, s63, v189
	v_add_u32_e32 v174, s64, v189
	ds_read_b128 v[128:131], v140
	ds_read_b128 v[132:135], v140 offset:1024
	ds_read_b128 v[136:139], v140 offset:2048
	ds_read_b128 v[140:143], v140 offset:3072
	ds_read_b128 v[144:147], v174
	ds_read_b128 v[148:151], v174 offset:1024
	ds_read_b128 v[170:173], v174 offset:2048
	ds_read_b128 v[174:177], v174 offset:3072
	s_add_u32 s36, s36, 0x40000
	s_addc_u32 s37, s37, 0
	s_mov_b32 m0, s41
	v_lshl_add_u64 v[240:241], s[36:37], 0, v[162:163]
	ds_read_b128 v[178:181], v192 offset:32768
	ds_read_b128 v[182:185], v192 offset:33792
	ds_read_b128 v[194:197], v192 offset:34816
	ds_read_b128 v[198:201], v192 offset:35840
	ds_read_b128 v[202:205], v192 offset:36864
	ds_read_b128 v[206:209], v192 offset:37888
	ds_read_b128 v[210:213], v192 offset:38912
	ds_read_b128 v[214:217], v192 offset:39936
	global_load_lds_dwordx4 v[240:241], off
	v_lshl_add_u64 v[240:241], s[36:37], 0, v[166:167]
	s_mov_b32 m0, s42
	s_nop 0
	global_load_lds_dwordx4 v[240:241], off
	s_waitcnt vmcnt(8)
	s_waitcnt lgkmcnt(0)
	s_barrier
	s_waitcnt lgkmcnt(0)
	v_mfma_f32_16x16x32_bf16 v[124:127], v[128:131], v[178:181], v[124:127]
	v_mfma_f32_16x16x32_bf16 v[120:123], v[136:139], v[178:181], v[120:123]
	v_mfma_f32_16x16x32_bf16 v[108:111], v[128:131], v[194:197], v[108:111]
	v_mfma_f32_16x16x32_bf16 v[104:107], v[136:139], v[194:197], v[104:107]
	v_mfma_f32_16x16x32_bf16 v[92:95], v[128:131], v[202:205], v[92:95]
	v_mfma_f32_16x16x32_bf16 v[88:91], v[136:139], v[202:205], v[88:91]
	v_mfma_f32_16x16x32_bf16 v[76:79], v[128:131], v[210:213], v[76:79]
	v_mfma_f32_16x16x32_bf16 v[72:75], v[136:139], v[210:213], v[72:75]
	v_mfma_f32_16x16x32_bf16 v[124:127], v[132:135], v[182:185], v[124:127]
	v_mfma_f32_16x16x32_bf16 v[120:123], v[140:143], v[182:185], v[120:123]
	v_mfma_f32_16x16x32_bf16 v[108:111], v[132:135], v[198:201], v[108:111]
	v_mfma_f32_16x16x32_bf16 v[104:107], v[140:143], v[198:201], v[104:107]
	v_mfma_f32_16x16x32_bf16 v[92:95], v[132:135], v[206:209], v[92:95]
	v_mfma_f32_16x16x32_bf16 v[88:91], v[140:143], v[206:209], v[88:91]
	v_mfma_f32_16x16x32_bf16 v[76:79], v[132:135], v[214:217], v[76:79]
	v_mfma_f32_16x16x32_bf16 v[72:75], v[140:143], v[214:217], v[72:75]
	v_mfma_f32_16x16x32_bf16 v[116:119], v[144:147], v[178:181], v[116:119]
	v_mfma_f32_16x16x32_bf16 v[112:115], v[170:173], v[178:181], v[112:115]
	v_mfma_f32_16x16x32_bf16 v[100:103], v[144:147], v[194:197], v[100:103]
	v_mfma_f32_16x16x32_bf16 v[96:99], v[170:173], v[194:197], v[96:99]
	v_mfma_f32_16x16x32_bf16 v[84:87], v[144:147], v[202:205], v[84:87]
	v_mfma_f32_16x16x32_bf16 v[80:83], v[170:173], v[202:205], v[80:83]
	v_mfma_f32_16x16x32_bf16 v[68:71], v[144:147], v[210:213], v[68:71]
	v_mfma_f32_16x16x32_bf16 v[64:67], v[170:173], v[210:213], v[64:67]
	v_mfma_f32_16x16x32_bf16 v[116:119], v[148:151], v[182:185], v[116:119]
	v_mfma_f32_16x16x32_bf16 v[112:115], v[174:177], v[182:185], v[112:115]
	v_mfma_f32_16x16x32_bf16 v[100:103], v[148:151], v[198:201], v[100:103]
	v_mfma_f32_16x16x32_bf16 v[96:99], v[174:177], v[198:201], v[96:99]
	v_mfma_f32_16x16x32_bf16 v[84:87], v[148:151], v[206:209], v[84:87]
	v_mfma_f32_16x16x32_bf16 v[80:83], v[174:177], v[206:209], v[80:83]
	v_mfma_f32_16x16x32_bf16 v[68:71], v[148:151], v[214:217], v[68:71]
	v_mfma_f32_16x16x32_bf16 v[64:67], v[174:177], v[214:217], v[64:67]
	s_barrier
; #define PG8_STAGE(bufoff, gbase, voff) do { _Pragma("unroll") for (int _i = 0; _i < 2; ++_i) \
;         __builtin_amdgcn_global_load_lds((const unsigned*)((const char*)(gbase) + (voff)[_i]), (PG8_LAS unsigned*)(lds + (bufoff) + ldsw + _i * 8192), 16, 0, 0); } while (0)
; #define PG8_LDA(dst, b, h) do { _Pragma("unroll") for (int m = 0; m < 4; ++m) _Pragma("unroll") for (int k = 0; k < 2; ++k) dst[m][k] = *(const PG8_LAS bf16x8*)(lds + PG8_SA(b, h) + aoff + m * 2048 + k * 1024); } while (0)
; #define PG8_MMA(ai, bj, At, Bt) do { __builtin_amdgcn_s_setprio(1); _Pragma("unroll") for (int m = 0; m < 4; ++m) _Pragma("unroll") for (int n = 0; n < 2; ++n) _Pragma("unroll") for (int k = 0; k < 2; ++k) \
;         acc[ai][bj][m][n] = mma16<F16>(Bt[n][k], At[m][k], acc[ai][bj][m][n]); __builtin_amdgcn_s_setprio(0); } while (0)
; #define PG8_WAIT_V(n) asm volatile("s_waitcnt vmcnt(" #n ")" ::: "memory")
; #define PG8_WAIT_L(n) asm volatile("s_waitcnt lgkmcnt(" #n ")" ::: "memory")
; #define PG8_BAR __builtin_amdgcn_s_barrier()
; #define PG8_SCHED __builtin_amdgcn_sched_barrier(0)
; template <class Epi, class Sched, bool ALIGN_EPI = false, bool SP2 = false, bool F16 = false>
; __device__ __forceinline__ void gemm_phase(PG8_LAS unsigned char* lds, const Gemm g, const Sched& S, const Epi& E) {
;     ...
;             PG8_LDA(At, 1, 1); PG8_STAGE(PG8_SB(1, 0), b3, voffB); PG8_STAGE(PG8_SB(1, 1), b3 + hstep, voffB); PG8_STAGE(PG8_SA(1, 0), a3, voffA);
;             PG8_WAIT_V(8); PG8_WAIT_L(0); PG8_BAR; PG8_MMA(1, 0, At, B0); PG8_MMA(1, 1, At, B1); PG8_BAR; PG8_SCHED;
	s_add_i32 s36, s63, s39
	v_lshl_add_u64 v[186:187], v[186:187], 0, s[14:15]
	s_mov_b32 m0, s36
	ds_read_b128 v[178:181], v192 offset:49152
	ds_read_b128 v[182:185], v192 offset:50176
	ds_read_b128 v[194:197], v192 offset:51200
	ds_read_b128 v[198:201], v192 offset:52224
	ds_read_b128 v[202:205], v192 offset:53248
	ds_read_b128 v[206:209], v192 offset:54272
	ds_read_b128 v[210:213], v192 offset:55296
	ds_read_b128 v[214:217], v192 offset:56320
	global_load_lds_dwordx4 v[186:187], off
	s_add_i32 m0, s36, 0x2000
	s_add_u32 s34, s34, 0x40080
	v_lshl_add_u64 v[186:187], v[218:219], 0, s[14:15]
	s_addc_u32 s35, s35, 0
	s_add_i32 s36, s64, s39
	global_load_lds_dwordx4 v[186:187], off
	v_lshl_add_u64 v[186:187], s[34:35], 0, v[164:165]
	s_mov_b32 m0, s36
	s_nop 0
	global_load_lds_dwordx4 v[186:187], off
	v_lshl_add_u64 v[186:187], s[34:35], 0, v[168:169]
	s_add_i32 m0, s36, 0x2000
	s_nop 0
	global_load_lds_dwordx4 v[186:187], off
	v_lshl_add_u64 v[186:187], v[220:221], 0, s[14:15]
	s_mov_b32 m0, s44
	s_nop 0
	global_load_lds_dwordx4 v[186:187], off
	v_lshl_add_u64 v[186:187], v[222:223], 0, s[14:15]
	s_mov_b32 m0, s45
	s_nop 0
	global_load_lds_dwordx4 v[186:187], off
	s_waitcnt vmcnt(8)
	s_waitcnt lgkmcnt(0)
	s_barrier
	s_waitcnt lgkmcnt(0)
	v_mfma_f32_16x16x32_bf16 v[60:63], v[128:131], v[178:181], v[60:63]
	v_mfma_f32_16x16x32_bf16 v[56:59], v[136:139], v[178:181], v[56:59]
	v_mfma_f32_16x16x32_bf16 v[44:47], v[128:131], v[194:197], v[44:47]
	v_mfma_f32_16x16x32_bf16 v[40:43], v[136:139], v[194:197], v[40:43]
	v_mfma_f32_16x16x32_bf16 v[28:31], v[128:131], v[202:205], v[28:31]
	v_mfma_f32_16x16x32_bf16 v[24:27], v[136:139], v[202:205], v[24:27]
	v_mfma_f32_16x16x32_bf16 v[12:15], v[128:131], v[210:213], v[12:15]
	v_mfma_f32_16x16x32_bf16 v[8:11], v[136:139], v[210:213], v[8:11]
	v_mfma_f32_16x16x32_bf16 v[60:63], v[132:135], v[182:185], v[60:63]
	v_mfma_f32_16x16x32_bf16 v[56:59], v[140:143], v[182:185], v[56:59]
	v_mfma_f32_16x16x32_bf16 v[44:47], v[132:135], v[198:201], v[44:47]
	v_mfma_f32_16x16x32_bf16 v[40:43], v[140:143], v[198:201], v[40:43]
	v_mfma_f32_16x16x32_bf16 v[28:31], v[132:135], v[206:209], v[28:31]
	v_mfma_f32_16x16x32_bf16 v[24:27], v[140:143], v[206:209], v[24:27]
	v_mfma_f32_16x16x32_bf16 v[12:15], v[132:135], v[214:217], v[12:15]
	v_mfma_f32_16x16x32_bf16 v[8:11], v[140:143], v[214:217], v[8:11]
	v_mfma_f32_16x16x32_bf16 v[52:55], v[144:147], v[178:181], v[52:55]
	v_mfma_f32_16x16x32_bf16 v[48:51], v[170:173], v[178:181], v[48:51]
	v_mfma_f32_16x16x32_bf16 v[36:39], v[144:147], v[194:197], v[36:39]
	v_mfma_f32_16x16x32_bf16 v[32:35], v[170:173], v[194:197], v[32:35]
	v_mfma_f32_16x16x32_bf16 v[20:23], v[144:147], v[202:205], v[20:23]
	v_mfma_f32_16x16x32_bf16 v[16:19], v[170:173], v[202:205], v[16:19]
	v_mfma_f32_16x16x32_bf16 v[4:7], v[144:147], v[210:213], v[4:7]
	v_mfma_f32_16x16x32_bf16 v[0:3], v[170:173], v[210:213], v[0:3]
	v_mfma_f32_16x16x32_bf16 v[52:55], v[148:151], v[182:185], v[52:55]
	v_mfma_f32_16x16x32_bf16 v[48:51], v[174:177], v[182:185], v[48:51]
	v_mfma_f32_16x16x32_bf16 v[36:39], v[148:151], v[198:201], v[36:39]
	v_mfma_f32_16x16x32_bf16 v[32:35], v[174:177], v[198:201], v[32:35]
	v_mfma_f32_16x16x32_bf16 v[20:23], v[148:151], v[206:209], v[20:23]
	v_mfma_f32_16x16x32_bf16 v[16:19], v[174:177], v[206:209], v[16:19]
	v_mfma_f32_16x16x32_bf16 v[4:7], v[148:151], v[214:217], v[4:7]
	v_mfma_f32_16x16x32_bf16 v[0:3], v[174:177], v[214:217], v[0:3]
	s_barrier
	s_add_i32 s62, s62, 2
	s_add_u32 s30, s30, 0x100
	s_addc_u32 s31, s31, 0
	s_add_u32 s60, s60, 0x100
	s_addc_u32 s61, s61, 0
	s_cmp_gt_u32 s62, 13
	s_cbranch_scc0 .LBB0_582
	s_and_b64 vcc, exec, s[16:17]
	s_cbranch_vccz .LBB0_585
	s_barrier

; #define PG8_STAGE(bufoff, gbase, voff) do { _Pragma("unroll") for (int _i = 0; _i < 2; ++_i) \
;         __builtin_amdgcn_global_load_lds((const unsigned*)((const char*)(gbase) + (voff)[_i]), (PG8_LAS unsigned*)(lds + (bufoff) + ldsw + _i * 8192), 16, 0, 0); } while (0)
; #define PG8_LDA(dst, b, h) do { _Pragma("unroll") for (int m = 0; m < 4; ++m) _Pragma("unroll") for (int k = 0; k < 2; ++k) dst[m][k] = *(const PG8_LAS bf16x8*)(lds + PG8_SA(b, h) + aoff + m * 2048 + k * 1024); } while (0)
; #define PG8_LDB(dst, b, h) do { _Pragma("unroll") for (int n = 0; n < 2; ++n) _Pragma("unroll") for (int k = 0; k < 2; ++k) dst[n][k] = *(const PG8_LAS bf16x8*)(lds + PG8_SB(b, h) + boff + n * 2048 + k * 1024); } while (0)
; #define PG8_MMA(ai, bj, At, Bt) do { __builtin_amdgcn_s_setprio(1); _Pragma("unroll") for (int m = 0; m < 4; ++m) _Pragma("unroll") for (int n = 0; n < 2; ++n) _Pragma("unroll") for (int k = 0; k < 2; ++k) \
;         acc[ai][bj][m][n] = mma16<F16>(Bt[n][k], At[m][k], acc[ai][bj][m][n]); __builtin_amdgcn_s_setprio(0); } while (0)
; #define PG8_WAIT_V(n) asm volatile("s_waitcnt vmcnt(" #n ")" ::: "memory")
; #define PG8_WAIT_L(n) asm volatile("s_waitcnt lgkmcnt(" #n ")" ::: "memory")
; #define PG8_BAR __builtin_amdgcn_s_barrier()
; #define PG8_SCHED __builtin_amdgcn_sched_barrier(0)
; template <class Epi, class Sched, bool ALIGN_EPI = false, bool SP2 = false, bool F16 = false>
; __device__ __forceinline__ void gemm_phase(PG8_LAS unsigned char* lds, const Gemm g, const Sched& S, const Epi& E) {
;     ...
;             PG8_LDB(B0, 0, 0); PG8_LDB(B1, 0, 1); PG8_SCHED; PG8_LDA(At, 0, 0); PG8_STAGE(PG8_SA(1, 1), a1 + hstep, voffA);
;             PG8_WAIT_V(8); PG8_WAIT_L(0); PG8_BAR; PG8_MMA(0, 0, At, B0); PG8_MMA(0, 1, At, B1); PG8_BAR; PG8_SCHED;
;             PG8_LDA(At, 0, 1); PG8_STAGE(PG8_SB(0, 0), b2, voffB); PG8_STAGE(PG8_SB(0, 1), b2 + hstep, voffB); PG8_STAGE(PG8_SA(0, 0), a2, voffA);
;             PG8_WAIT_V(8); PG8_WAIT_L(0); PG8_BAR; PG8_MMA(1, 0, At, B0); PG8_MMA(1, 1, At, B1); PG8_BAR; PG8_SCHED;
.LBB0_666:
	ds_read_b128 v[146:149], v141
	ds_read_b128 v[150:153], v141 offset:1024
	ds_read_b128 v[154:157], v141 offset:2048
	ds_read_b128 v[170:173], v141 offset:3072
	ds_read_b128 v[174:177], v142
	ds_read_b128 v[178:181], v142 offset:1024
	ds_read_b128 v[182:185], v142 offset:2048
	ds_read_b128 v[186:189], v142 offset:3072
	s_add_u32 s28, s26, 0xfffc0080
	s_addc_u32 s29, s27, -1
	s_cmp_eq_u32 s60, 12
	s_cselect_b32 s31, s19, s29
	s_cselect_b32 s30, s52, s28
	s_cselect_b32 s29, s17, s55
	s_cselect_b32 s28, s53, s54
	v_lshl_add_u64 v[136:137], s[26:27], 0, v[128:129]
	s_add_i32 m0, s25, 0xc000
	ds_read_b128 v[190:193], v143
	ds_read_b128 v[194:197], v143 offset:1024
	ds_read_b128 v[198:201], v143 offset:2048
	ds_read_b128 v[202:205], v143 offset:3072
	ds_read_b128 v[206:209], v143 offset:4096
	ds_read_b128 v[210:213], v143 offset:5120
	ds_read_b128 v[214:217], v143 offset:6144
	ds_read_b128 v[218:221], v143 offset:7168
	global_load_lds_dwordx4 v[136:137], off
	v_lshl_add_u64 v[136:137], s[26:27], 0, v[130:131]
	s_add_i32 m0, s25, 0xe000
	s_nop 0
	global_load_lds_dwordx4 v[136:137], off
	s_waitcnt vmcnt(8)
	s_waitcnt lgkmcnt(0)
	s_barrier
	s_waitcnt lgkmcnt(0)
	v_mfma_f32_16x16x32_f16 v[116:119], v[146:149], v[190:193], v[116:119]
	v_mfma_f32_16x16x32_f16 v[112:115], v[154:157], v[190:193], v[112:115]
	v_mfma_f32_16x16x32_f16 v[108:111], v[146:149], v[198:201], v[108:111]
	v_mfma_f32_16x16x32_f16 v[100:103], v[154:157], v[198:201], v[100:103]
	v_mfma_f32_16x16x32_f16 v[92:95], v[146:149], v[206:209], v[92:95]
	v_mfma_f32_16x16x32_f16 v[84:87], v[154:157], v[206:209], v[84:87]
	v_mfma_f32_16x16x32_f16 v[76:79], v[146:149], v[214:217], v[76:79]
	v_mfma_f32_16x16x32_f16 v[68:71], v[154:157], v[214:217], v[68:71]
	v_mfma_f32_16x16x32_f16 v[116:119], v[150:153], v[194:197], v[116:119]
	v_mfma_f32_16x16x32_f16 v[112:115], v[170:173], v[194:197], v[112:115]
	v_mfma_f32_16x16x32_f16 v[108:111], v[150:153], v[202:205], v[108:111]
	v_mfma_f32_16x16x32_f16 v[100:103], v[170:173], v[202:205], v[100:103]
	v_mfma_f32_16x16x32_f16 v[92:95], v[150:153], v[210:213], v[92:95]
	v_mfma_f32_16x16x32_f16 v[84:87], v[170:173], v[210:213], v[84:87]
	v_mfma_f32_16x16x32_f16 v[76:79], v[150:153], v[218:221], v[76:79]
	v_mfma_f32_16x16x32_f16 v[68:71], v[170:173], v[218:221], v[68:71]
	v_mfma_f32_16x16x32_f16 v[124:127], v[174:177], v[190:193], v[124:127]
	v_mfma_f32_16x16x32_f16 v[120:123], v[182:185], v[190:193], v[120:123]
	v_mfma_f32_16x16x32_f16 v[104:107], v[174:177], v[198:201], v[104:107]
	v_mfma_f32_16x16x32_f16 v[96:99], v[182:185], v[198:201], v[96:99]
	v_mfma_f32_16x16x32_f16 v[88:91], v[174:177], v[206:209], v[88:91]
	v_mfma_f32_16x16x32_f16 v[80:83], v[182:185], v[206:209], v[80:83]
	v_mfma_f32_16x16x32_f16 v[72:75], v[174:177], v[214:217], v[72:75]
	v_mfma_f32_16x16x32_f16 v[64:67], v[182:185], v[214:217], v[64:67]
	v_mfma_f32_16x16x32_f16 v[124:127], v[178:181], v[194:197], v[124:127]
	v_mfma_f32_16x16x32_f16 v[120:123], v[186:189], v[194:197], v[120:123]
	v_mfma_f32_16x16x32_f16 v[104:107], v[178:181], v[202:205], v[104:107]
	v_mfma_f32_16x16x32_f16 v[96:99], v[186:189], v[202:205], v[96:99]
	v_mfma_f32_16x16x32_f16 v[88:91], v[178:181], v[210:213], v[88:91]
	v_mfma_f32_16x16x32_f16 v[80:83], v[186:189], v[210:213], v[80:83]
	v_mfma_f32_16x16x32_f16 v[72:75], v[178:181], v[218:221], v[72:75]
	v_mfma_f32_16x16x32_f16 v[64:67], v[186:189], v[218:221], v[64:67]
	s_barrier
	s_add_i32 s61, s46, s35
	v_lshl_add_u64 v[136:137], s[28:29], 0, v[164:165]
	s_mov_b32 m0, s61
	ds_read_b128 v[190:193], v143 offset:16384
	ds_read_b128 v[194:197], v143 offset:17408
	ds_read_b128 v[198:201], v143 offset:18432
	ds_read_b128 v[202:205], v143 offset:19456
	ds_read_b128 v[206:209], v143 offset:20480
	ds_read_b128 v[210:213], v143 offset:21504
	ds_read_b128 v[214:217], v143 offset:22528
	ds_read_b128 v[218:221], v143 offset:23552
	global_load_lds_dwordx4 v[136:137], off
	s_add_i32 m0, s61, 0x2000
	s_add_u32 s62, s28, 0x40000
	v_lshl_add_u64 v[158:159], s[28:29], 0, v[168:169]
	s_addc_u32 s63, s29, 0
	s_add_i32 s61, s47, s35
	global_load_lds_dwordx4 v[158:159], off
	v_lshl_add_u64 v[222:223], s[62:63], 0, v[164:165]
	s_mov_b32 m0, s61
	v_lshl_add_u64 v[236:237], s[30:31], 0, v[166:167]
	global_load_lds_dwordx4 v[222:223], off
	v_lshl_add_u64 v[222:223], s[62:63], 0, v[168:169]
	s_add_i32 m0, s61, 0x2000
	s_nop 0
	global_load_lds_dwordx4 v[222:223], off
	v_lshl_add_u64 v[222:223], s[30:31], 0, v[162:163]
	s_mov_b32 m0, s25
	s_nop 0
	global_load_lds_dwordx4 v[222:223], off
	s_mov_b32 m0, s38
	s_nop 0
	global_load_lds_dwordx4 v[236:237], off
	s_waitcnt vmcnt(8)
	s_waitcnt lgkmcnt(0)
	s_barrier
; #define PG8_STAGE(bufoff, gbase, voff) do { _Pragma("unroll") for (int _i = 0; _i < 2; ++_i) \
;         __builtin_amdgcn_global_load_lds((const unsigned*)((const char*)(gbase) + (voff)[_i]), (PG8_LAS unsigned*)(lds + (bufoff) + ldsw + _i * 8192), 16, 0, 0); } while (0)
; #define PG8_LDA(dst, b, h) do { _Pragma("unroll") for (int m = 0; m < 4; ++m) _Pragma("unroll") for (int k = 0; k < 2; ++k) dst[m][k] = *(const PG8_LAS bf16x8*)(lds + PG8_SA(b, h) + aoff + m * 2048 + k * 1024); } while (0)
; #define PG8_LDB(dst, b, h) do { _Pragma("unroll") for (int n = 0; n < 2; ++n) _Pragma("unroll") for (int k = 0; k < 2; ++k) dst[n][k] = *(const PG8_LAS bf16x8*)(lds + PG8_SB(b, h) + boff + n * 2048 + k * 1024); } while (0)
; #define PG8_MMA(ai, bj, At, Bt) do { __builtin_amdgcn_s_setprio(1); _Pragma("unroll") for (int m = 0; m < 4; ++m) _Pragma("unroll") for (int n = 0; n < 2; ++n) _Pragma("unroll") for (int k = 0; k < 2; ++k) \
;         acc[ai][bj][m][n] = mma16<F16>(Bt[n][k], At[m][k], acc[ai][bj][m][n]); __builtin_amdgcn_s_setprio(0); } while (0)
; #define PG8_WAIT_V(n) asm volatile("s_waitcnt vmcnt(" #n ")" ::: "memory")
; #define PG8_WAIT_L(n) asm volatile("s_waitcnt lgkmcnt(" #n ")" ::: "memory")
; #define PG8_BAR __builtin_amdgcn_s_barrier()
; #define PG8_SCHED __builtin_amdgcn_sched_barrier(0)
; template <class Epi, class Sched, bool ALIGN_EPI = false, bool SP2 = false, bool F16 = false>
; __device__ __forceinline__ void gemm_phase(PG8_LAS unsigned char* lds, const Gemm g, const Sched& S, const Epi& E) {
;     ...
;             PG8_WAIT_V(8); PG8_WAIT_L(0); PG8_BAR; PG8_MMA(1, 0, At, B0); PG8_MMA(1, 1, At, B1); PG8_BAR; PG8_SCHED;
;             PG8_LDB(B0, 1, 0); PG8_LDB(B1, 1, 1); PG8_SCHED; PG8_LDA(At, 1, 0); PG8_STAGE(PG8_SA(0, 1), a2 + hstep, voffA);
;             PG8_WAIT_V(8); PG8_WAIT_L(0); PG8_BAR; PG8_MMA(0, 0, At, B0); PG8_MMA(0, 1, At, B1); PG8_BAR; PG8_SCHED;
	s_waitcnt lgkmcnt(0)
	v_mfma_f32_16x16x32_f16 v[60:63], v[146:149], v[190:193], v[60:63]
	v_mfma_f32_16x16x32_f16 v[52:55], v[154:157], v[190:193], v[52:55]
	v_mfma_f32_16x16x32_f16 v[44:47], v[146:149], v[198:201], v[44:47]
	v_mfma_f32_16x16x32_f16 v[36:39], v[154:157], v[198:201], v[36:39]
	v_mfma_f32_16x16x32_f16 v[28:31], v[146:149], v[206:209], v[28:31]
	v_mfma_f32_16x16x32_f16 v[20:23], v[154:157], v[206:209], v[20:23]
	v_mfma_f32_16x16x32_f16 v[12:15], v[146:149], v[214:217], v[12:15]
	v_mfma_f32_16x16x32_f16 v[4:7], v[154:157], v[214:217], v[4:7]
	v_mfma_f32_16x16x32_f16 v[60:63], v[150:153], v[194:197], v[60:63]
	v_mfma_f32_16x16x32_f16 v[52:55], v[170:173], v[194:197], v[52:55]
	v_mfma_f32_16x16x32_f16 v[44:47], v[150:153], v[202:205], v[44:47]
	v_mfma_f32_16x16x32_f16 v[36:39], v[170:173], v[202:205], v[36:39]
	v_mfma_f32_16x16x32_f16 v[28:31], v[150:153], v[210:213], v[28:31]
	v_mfma_f32_16x16x32_f16 v[20:23], v[170:173], v[210:213], v[20:23]
	v_mfma_f32_16x16x32_f16 v[12:15], v[150:153], v[218:221], v[12:15]
	v_mfma_f32_16x16x32_f16 v[4:7], v[170:173], v[218:221], v[4:7]
	v_mfma_f32_16x16x32_f16 v[56:59], v[174:177], v[190:193], v[56:59]
	v_mfma_f32_16x16x32_f16 v[48:51], v[182:185], v[190:193], v[48:51]
	v_mfma_f32_16x16x32_f16 v[40:43], v[174:177], v[198:201], v[40:43]
	v_mfma_f32_16x16x32_f16 v[32:35], v[182:185], v[198:201], v[32:35]
	v_mfma_f32_16x16x32_f16 v[24:27], v[174:177], v[206:209], v[24:27]
	v_mfma_f32_16x16x32_f16 v[16:19], v[182:185], v[206:209], v[16:19]
	v_mfma_f32_16x16x32_f16 v[8:11], v[174:177], v[214:217], v[8:11]
	v_mfma_f32_16x16x32_f16 v[0:3], v[182:185], v[214:217], v[0:3]
	v_mfma_f32_16x16x32_f16 v[56:59], v[178:181], v[194:197], v[56:59]
	v_mfma_f32_16x16x32_f16 v[48:51], v[186:189], v[194:197], v[48:51]
	v_mfma_f32_16x16x32_f16 v[40:43], v[178:181], v[202:205], v[40:43]
	v_mfma_f32_16x16x32_f16 v[32:35], v[186:189], v[202:205], v[32:35]
	v_mfma_f32_16x16x32_f16 v[24:27], v[178:181], v[210:213], v[24:27]
	v_mfma_f32_16x16x32_f16 v[16:19], v[186:189], v[210:213], v[16:19]
	v_mfma_f32_16x16x32_f16 v[8:11], v[178:181], v[218:221], v[8:11]
	v_mfma_f32_16x16x32_f16 v[0:3], v[186:189], v[218:221], v[0:3]
	s_barrier
	s_add_i32 s61, 0, 0x18000
	v_add_u32_e32 v145, s61, v139
	s_add_i32 s62, 0, 0x1c000
	ds_read_b128 v[146:149], v145
	ds_read_b128 v[150:153], v145 offset:1024
	ds_read_b128 v[154:157], v145 offset:2048
	ds_read_b128 v[170:173], v145 offset:3072
	v_add_u32_e32 v145, s62, v139
	ds_read_b128 v[174:177], v145
	ds_read_b128 v[178:181], v145 offset:1024
	ds_read_b128 v[182:185], v145 offset:2048
	ds_read_b128 v[186:189], v145 offset:3072
	s_add_u32 s30, s30, 0x40000
	s_addc_u32 s31, s31, 0
	s_mov_b32 m0, s39
	v_lshl_add_u64 v[238:239], s[30:31], 0, v[162:163]
	ds_read_b128 v[190:193], v143 offset:32768
	ds_read_b128 v[194:197], v143 offset:33792
	ds_read_b128 v[198:201], v143 offset:34816
	ds_read_b128 v[202:205], v143 offset:35840
	ds_read_b128 v[206:209], v143 offset:36864
	ds_read_b128 v[210:213], v143 offset:37888
	ds_read_b128 v[214:217], v143 offset:38912
	ds_read_b128 v[218:221], v143 offset:39936
	global_load_lds_dwordx4 v[238:239], off
	v_lshl_add_u64 v[238:239], s[30:31], 0, v[166:167]
	s_mov_b32 m0, s40
	s_nop 0
	global_load_lds_dwordx4 v[238:239], off
	s_waitcnt vmcnt(8)
	s_waitcnt lgkmcnt(0)
	s_barrier
	s_waitcnt lgkmcnt(0)
	v_mfma_f32_16x16x32_f16 v[116:119], v[146:149], v[190:193], v[116:119]
	v_mfma_f32_16x16x32_f16 v[112:115], v[154:157], v[190:193], v[112:115]
	v_mfma_f32_16x16x32_f16 v[108:111], v[146:149], v[198:201], v[108:111]
	v_mfma_f32_16x16x32_f16 v[100:103], v[154:157], v[198:201], v[100:103]
	v_mfma_f32_16x16x32_f16 v[92:95], v[146:149], v[206:209], v[92:95]
	v_mfma_f32_16x16x32_f16 v[84:87], v[154:157], v[206:209], v[84:87]
	v_mfma_f32_16x16x32_f16 v[76:79], v[146:149], v[214:217], v[76:79]
	v_mfma_f32_16x16x32_f16 v[68:71], v[154:157], v[214:217], v[68:71]
	v_mfma_f32_16x16x32_f16 v[116:119], v[150:153], v[194:197], v[116:119]
	v_mfma_f32_16x16x32_f16 v[112:115], v[170:173], v[194:197], v[112:115]
	v_mfma_f32_16x16x32_f16 v[108:111], v[150:153], v[202:205], v[108:111]
	v_mfma_f32_16x16x32_f16 v[100:103], v[170:173], v[202:205], v[100:103]
	v_mfma_f32_16x16x32_f16 v[92:95], v[150:153], v[210:213], v[92:95]
	v_mfma_f32_16x16x32_f16 v[84:87], v[170:173], v[210:213], v[84:87]
	v_mfma_f32_16x16x32_f16 v[76:79], v[150:153], v[218:221], v[76:79]
	v_mfma_f32_16x16x32_f16 v[68:71], v[170:173], v[218:221], v[68:71]
	v_mfma_f32_16x16x32_f16 v[124:127], v[174:177], v[190:193], v[124:127]
	v_mfma_f32_16x16x32_f16 v[120:123], v[182:185], v[190:193], v[120:123]
	v_mfma_f32_16x16x32_f16 v[104:107], v[174:177], v[198:201], v[104:107]
	v_mfma_f32_16x16x32_f16 v[96:99], v[182:185], v[198:201], v[96:99]
	v_mfma_f32_16x16x32_f16 v[88:91], v[174:177], v[206:209], v[88:91]
	v_mfma_f32_16x16x32_f16 v[80:83], v[182:185], v[206:209], v[80:83]
	v_mfma_f32_16x16x32_f16 v[72:75], v[174:177], v[214:217], v[72:75]
	v_mfma_f32_16x16x32_f16 v[64:67], v[182:185], v[214:217], v[64:67]
	v_mfma_f32_16x16x32_f16 v[124:127], v[178:181], v[194:197], v[124:127]
	v_mfma_f32_16x16x32_f16 v[120:123], v[186:189], v[194:197], v[120:123]
	v_mfma_f32_16x16x32_f16 v[104:107], v[178:181], v[202:205], v[104:107]
	v_mfma_f32_16x16x32_f16 v[96:99], v[186:189], v[202:205], v[96:99]
	v_mfma_f32_16x16x32_f16 v[88:91], v[178:181], v[210:213], v[88:91]
	v_mfma_f32_16x16x32_f16 v[80:83], v[186:189], v[210:213], v[80:83]
	v_mfma_f32_16x16x32_f16 v[72:75], v[178:181], v[218:221], v[72:75]
	v_mfma_f32_16x16x32_f16 v[64:67], v[186:189], v[218:221], v[64:67]
	s_barrier
; #define PG8_STAGE(bufoff, gbase, voff) do { _Pragma("unroll") for (int _i = 0; _i < 2; ++_i) \
;         __builtin_amdgcn_global_load_lds((const unsigned*)((const char*)(gbase) + (voff)[_i]), (PG8_LAS unsigned*)(lds + (bufoff) + ldsw + _i * 8192), 16, 0, 0); } while (0)
; #define PG8_LDA(dst, b, h) do { _Pragma("unroll") for (int m = 0; m < 4; ++m) _Pragma("unroll") for (int k = 0; k < 2; ++k) dst[m][k] = *(const PG8_LAS bf16x8*)(lds + PG8_SA(b, h) + aoff + m * 2048 + k * 1024); } while (0)
; #define PG8_MMA(ai, bj, At, Bt) do { __builtin_amdgcn_s_setprio(1); _Pragma("unroll") for (int m = 0; m < 4; ++m) _Pragma("unroll") for (int n = 0; n < 2; ++n) _Pragma("unroll") for (int k = 0; k < 2; ++k) \
;         acc[ai][bj][m][n] = mma16<F16>(Bt[n][k], At[m][k], acc[ai][bj][m][n]); __builtin_amdgcn_s_setprio(0); } while (0)
; #define PG8_WAIT_V(n) asm volatile("s_waitcnt vmcnt(" #n ")" ::: "memory")
; #define PG8_WAIT_L(n) asm volatile("s_waitcnt lgkmcnt(" #n ")" ::: "memory")
; #define PG8_BAR __builtin_amdgcn_s_barrier()
; #define PG8_SCHED __builtin_amdgcn_sched_barrier(0)
; template <class Epi, class Sched, bool ALIGN_EPI = false, bool SP2 = false, bool F16 = false>
; __device__ __forceinline__ void gemm_phase(PG8_LAS unsigned char* lds, const Gemm g, const Sched& S, const Epi& E) {
;     ...
;         for (int t = 0; t < nt; t += 2) {
;             const bool last = (t == nt - 2);
;     ...
;             PG8_LDA(At, 1, 1); PG8_STAGE(PG8_SB(1, 0), b3, voffB); PG8_STAGE(PG8_SB(1, 1), b3 + hstep, voffB); PG8_STAGE(PG8_SA(1, 0), a3, voffA);
;             PG8_WAIT_V(8); PG8_WAIT_L(0); PG8_BAR; PG8_MMA(1, 0, At, B0); PG8_MMA(1, 1, At, B1); PG8_BAR; PG8_SCHED;
;     ...
;         if constexpr (ALIGN_EPI) { if (wr == 0) PG8_BAR; }
	s_add_i32 s30, s61, s35
	v_lshl_add_u64 v[136:137], v[136:137], 0, s[12:13]
	s_mov_b32 m0, s30
	ds_read_b128 v[190:193], v143 offset:49152
	ds_read_b128 v[194:197], v143 offset:50176
	ds_read_b128 v[198:201], v143 offset:51200
	ds_read_b128 v[202:205], v143 offset:52224
	ds_read_b128 v[206:209], v143 offset:53248
	ds_read_b128 v[210:213], v143 offset:54272
	ds_read_b128 v[214:217], v143 offset:55296
	ds_read_b128 v[218:221], v143 offset:56320
	global_load_lds_dwordx4 v[136:137], off
	s_add_i32 m0, s30, 0x2000
	s_add_u32 s28, s28, 0x40080
	v_lshl_add_u64 v[136:137], v[158:159], 0, s[12:13]
	s_addc_u32 s29, s29, 0
	s_add_i32 s30, s62, s35
	global_load_lds_dwordx4 v[136:137], off
	v_lshl_add_u64 v[136:137], s[28:29], 0, v[164:165]
	s_mov_b32 m0, s30
	s_nop 0
	global_load_lds_dwordx4 v[136:137], off
	v_lshl_add_u64 v[136:137], s[28:29], 0, v[168:169]
	s_add_i32 m0, s30, 0x2000
	s_nop 0
	global_load_lds_dwordx4 v[136:137], off
	v_lshl_add_u64 v[136:137], v[222:223], 0, s[12:13]
	s_mov_b32 m0, s42
	s_nop 0
	global_load_lds_dwordx4 v[136:137], off
	v_lshl_add_u64 v[136:137], v[236:237], 0, s[12:13]
	s_mov_b32 m0, s43
	s_nop 0
	global_load_lds_dwordx4 v[136:137], off
	s_waitcnt vmcnt(8)
	s_waitcnt lgkmcnt(0)
	s_barrier
	s_waitcnt lgkmcnt(0)
	v_mfma_f32_16x16x32_f16 v[60:63], v[146:149], v[190:193], v[60:63]
	v_mfma_f32_16x16x32_f16 v[52:55], v[154:157], v[190:193], v[52:55]
	v_mfma_f32_16x16x32_f16 v[44:47], v[146:149], v[198:201], v[44:47]
	v_mfma_f32_16x16x32_f16 v[36:39], v[154:157], v[198:201], v[36:39]
	v_mfma_f32_16x16x32_f16 v[28:31], v[146:149], v[206:209], v[28:31]
	v_mfma_f32_16x16x32_f16 v[20:23], v[154:157], v[206:209], v[20:23]
	v_mfma_f32_16x16x32_f16 v[12:15], v[146:149], v[214:217], v[12:15]
	v_mfma_f32_16x16x32_f16 v[4:7], v[154:157], v[214:217], v[4:7]
	v_mfma_f32_16x16x32_f16 v[60:63], v[150:153], v[194:197], v[60:63]
	v_mfma_f32_16x16x32_f16 v[52:55], v[170:173], v[194:197], v[52:55]
	v_mfma_f32_16x16x32_f16 v[44:47], v[150:153], v[202:205], v[44:47]
	v_mfma_f32_16x16x32_f16 v[36:39], v[170:173], v[202:205], v[36:39]
	v_mfma_f32_16x16x32_f16 v[28:31], v[150:153], v[210:213], v[28:31]
	v_mfma_f32_16x16x32_f16 v[20:23], v[170:173], v[210:213], v[20:23]
	v_mfma_f32_16x16x32_f16 v[12:15], v[150:153], v[218:221], v[12:15]
	v_mfma_f32_16x16x32_f16 v[4:7], v[170:173], v[218:221], v[4:7]
	v_mfma_f32_16x16x32_f16 v[56:59], v[174:177], v[190:193], v[56:59]
	v_mfma_f32_16x16x32_f16 v[48:51], v[182:185], v[190:193], v[48:51]
	v_mfma_f32_16x16x32_f16 v[40:43], v[174:177], v[198:201], v[40:43]
	v_mfma_f32_16x16x32_f16 v[32:35], v[182:185], v[198:201], v[32:35]
	v_mfma_f32_16x16x32_f16 v[24:27], v[174:177], v[206:209], v[24:27]
	v_mfma_f32_16x16x32_f16 v[16:19], v[182:185], v[206:209], v[16:19]
	v_mfma_f32_16x16x32_f16 v[8:11], v[174:177], v[214:217], v[8:11]
	v_mfma_f32_16x16x32_f16 v[0:3], v[182:185], v[214:217], v[0:3]
	v_mfma_f32_16x16x32_f16 v[56:59], v[178:181], v[194:197], v[56:59]
	v_mfma_f32_16x16x32_f16 v[48:51], v[186:189], v[194:197], v[48:51]
	v_mfma_f32_16x16x32_f16 v[40:43], v[178:181], v[202:205], v[40:43]
	v_mfma_f32_16x16x32_f16 v[32:35], v[186:189], v[202:205], v[32:35]
	v_mfma_f32_16x16x32_f16 v[24:27], v[178:181], v[210:213], v[24:27]
	v_mfma_f32_16x16x32_f16 v[16:19], v[186:189], v[210:213], v[16:19]
	v_mfma_f32_16x16x32_f16 v[8:11], v[178:181], v[218:221], v[8:11]
	v_mfma_f32_16x16x32_f16 v[0:3], v[186:189], v[218:221], v[0:3]
	s_barrier
	s_add_i32 s60, s60, 2
	s_add_u32 s26, s26, 0x100
	s_addc_u32 s27, s27, 0
	s_add_u32 s54, s54, 0x100
	s_addc_u32 s55, s55, 0
	s_cmp_gt_u32 s60, 13
	s_cbranch_scc0 .LBB0_666
	s_and_b64 vcc, exec, s[14:15]
	s_cbranch_vccz .LBB0_669
	s_barrier

; #define PG8_STAGE(bufoff, gbase, voff) do { _Pragma("unroll") for (int _i = 0; _i < 2; ++_i) \
;         __builtin_amdgcn_global_load_lds((const unsigned*)((const char*)(gbase) + (voff)[_i]), (PG8_LAS unsigned*)(lds + (bufoff) + ldsw + _i * 8192), 16, 0, 0); } while (0)
; #define PG8_LDA(dst, b, h) do { _Pragma("unroll") for (int m = 0; m < 4; ++m) _Pragma("unroll") for (int k = 0; k < 2; ++k) dst[m][k] = *(const PG8_LAS bf16x8*)(lds + PG8_SA(b, h) + aoff + m * 2048 + k * 1024); } while (0)
; #define PG8_LDB(dst, b, h) do { _Pragma("unroll") for (int n = 0; n < 2; ++n) _Pragma("unroll") for (int k = 0; k < 2; ++k) dst[n][k] = *(const PG8_LAS bf16x8*)(lds + PG8_SB(b, h) + boff + n * 2048 + k * 1024); } while (0)
; #define PG8_MMA(ai, bj, At, Bt) do { __builtin_amdgcn_s_setprio(1); _Pragma("unroll") for (int m = 0; m < 4; ++m) _Pragma("unroll") for (int n = 0; n < 2; ++n) _Pragma("unroll") for (int k = 0; k < 2; ++k) \
;         acc[ai][bj][m][n] = mma16<F16>(Bt[n][k], At[m][k], acc[ai][bj][m][n]); __builtin_amdgcn_s_setprio(0); } while (0)
; #define PG8_WAIT_V(n) asm volatile("s_waitcnt vmcnt(" #n ")" ::: "memory")
; #define PG8_WAIT_L(n) asm volatile("s_waitcnt lgkmcnt(" #n ")" ::: "memory")
; template <class Epi, class Sched, bool ALIGN_EPI = false, bool SP2 = false, bool F16 = false>
; __device__ __forceinline__ void gemm_phase(PG8_LAS unsigned char* lds, const Gemm g, const Sched& S, const Epi& E) {
;     ...
;         for (int t = 0; t < nt; t += 2) {
;             const bool last = (t == nt - 2);
;             const char* a1 = cA + (size_t)(t + 1) * kstep;
;             const char* a2 = last ? nA : cA + (size_t)(t + 2) * kstep; const char* b2 = last ? nB : cB + (size_t)(t + 2) * kstep;
;             const char* a3 = a2 + kstep; const char* b3 = b2 + kstep;
;             if (last && has_next) S.a_ready(nxt);
;             if constexpr (SP2) {
;             PG8_LDB(B0, 0, 0); PG8_LDB(B1, 0, 1); PG8_SCHED; PG8_LDA(At, 0, 0); PG8_STAGE(PG8_SA(1, 1), a1 + hstep, voffA);
;             PG8_WAIT_V(8); PG8_WAIT_L(0); PG8_BAR; PG8_MMA(0, 0, At, B0); PG8_MMA(0, 1, At, B1); PG8_BAR; PG8_SCHED;
;             PG8_LDA(At, 0, 1); PG8_STAGE(PG8_SB(0, 0), b2, voffB); PG8_STAGE(PG8_SB(0, 1), b2 + hstep, voffB); PG8_STAGE(PG8_SA(0, 0), a2, voffA);
;             PG8_WAIT_V(8); PG8_WAIT_L(0); PG8_BAR; PG8_MMA(1, 0, At, B0); PG8_MMA(1, 1, At, B1); PG8_BAR; PG8_SCHED;
.LBB0_746:
	ds_read_b128 v[128:131], v167
	ds_read_b128 v[132:135], v167 offset:1024
	ds_read_b128 v[136:139], v167 offset:2048
	ds_read_b128 v[156:159], v167 offset:3072
	ds_read_b128 v[160:163], v168
	ds_read_b128 v[170:173], v168 offset:1024
	ds_read_b128 v[174:177], v168 offset:2048
	ds_read_b128 v[178:181], v168 offset:3072
	s_add_u32 s18, s16, 0xfff50080
	s_addc_u32 s19, s17, -1
	s_cmp_eq_u32 s42, 40
	s_cselect_b32 s21, s5, s19
	s_cselect_b32 s20, s4, s18
	s_cselect_b32 s19, s15, s41
	s_cselect_b32 s18, s14, s40
	v_lshl_add_u64 v[214:215], s[16:17], 0, v[148:149]
	s_add_i32 m0, s25, 0xc000
	ds_read_b128 v[182:185], v169
	ds_read_b128 v[186:189], v169 offset:1024
	ds_read_b128 v[190:193], v169 offset:2048
	ds_read_b128 v[194:197], v169 offset:3072
	ds_read_b128 v[198:201], v169 offset:4096
	ds_read_b128 v[202:205], v169 offset:5120
	ds_read_b128 v[206:209], v169 offset:6144
	ds_read_b128 v[210:213], v169 offset:7168
	global_load_lds_dwordx4 v[214:215], off
	v_lshl_add_u64 v[214:215], s[16:17], 0, v[150:151]
	s_add_i32 m0, s25, 0xe000
	s_nop 0
	global_load_lds_dwordx4 v[214:215], off
	s_waitcnt vmcnt(8)
	s_waitcnt lgkmcnt(0)
	s_barrier
	s_waitcnt lgkmcnt(0)
	v_mfma_f32_16x16x32_bf16 v[124:127], v[128:131], v[182:185], v[124:127]
	v_mfma_f32_16x16x32_bf16 v[120:123], v[136:139], v[182:185], v[120:123]
	v_mfma_f32_16x16x32_bf16 v[116:119], v[128:131], v[190:193], v[116:119]
	v_mfma_f32_16x16x32_bf16 v[112:115], v[136:139], v[190:193], v[112:115]
	v_mfma_f32_16x16x32_bf16 v[100:103], v[128:131], v[198:201], v[100:103]
	v_mfma_f32_16x16x32_bf16 v[88:91], v[136:139], v[198:201], v[88:91]
	v_mfma_f32_16x16x32_bf16 v[80:83], v[128:131], v[206:209], v[80:83]
	v_mfma_f32_16x16x32_bf16 v[72:75], v[136:139], v[206:209], v[72:75]
	v_mfma_f32_16x16x32_bf16 v[124:127], v[132:135], v[186:189], v[124:127]
	v_mfma_f32_16x16x32_bf16 v[120:123], v[156:159], v[186:189], v[120:123]
	v_mfma_f32_16x16x32_bf16 v[116:119], v[132:135], v[194:197], v[116:119]
	v_mfma_f32_16x16x32_bf16 v[112:115], v[156:159], v[194:197], v[112:115]
	v_mfma_f32_16x16x32_bf16 v[100:103], v[132:135], v[202:205], v[100:103]
	v_mfma_f32_16x16x32_bf16 v[88:91], v[156:159], v[202:205], v[88:91]
	v_mfma_f32_16x16x32_bf16 v[80:83], v[132:135], v[210:213], v[80:83]
	v_mfma_f32_16x16x32_bf16 v[72:75], v[156:159], v[210:213], v[72:75]
	v_mfma_f32_16x16x32_bf16 v[108:111], v[160:163], v[182:185], v[108:111]
	v_mfma_f32_16x16x32_bf16 v[104:107], v[174:177], v[182:185], v[104:107]
	v_mfma_f32_16x16x32_bf16 v[96:99], v[160:163], v[190:193], v[96:99]
	v_mfma_f32_16x16x32_bf16 v[92:95], v[174:177], v[190:193], v[92:95]
	v_mfma_f32_16x16x32_bf16 v[84:87], v[160:163], v[198:201], v[84:87]
	v_mfma_f32_16x16x32_bf16 v[76:79], v[174:177], v[198:201], v[76:79]
	v_mfma_f32_16x16x32_bf16 v[68:71], v[160:163], v[206:209], v[68:71]
	v_mfma_f32_16x16x32_bf16 v[64:67], v[174:177], v[206:209], v[64:67]
	v_mfma_f32_16x16x32_bf16 v[108:111], v[170:173], v[186:189], v[108:111]
	v_mfma_f32_16x16x32_bf16 v[104:107], v[178:181], v[186:189], v[104:107]
	v_mfma_f32_16x16x32_bf16 v[96:99], v[170:173], v[194:197], v[96:99]
	v_mfma_f32_16x16x32_bf16 v[92:95], v[178:181], v[194:197], v[92:95]
	v_mfma_f32_16x16x32_bf16 v[84:87], v[170:173], v[202:205], v[84:87]
	v_mfma_f32_16x16x32_bf16 v[76:79], v[178:181], v[202:205], v[76:79]
	v_mfma_f32_16x16x32_bf16 v[68:71], v[170:173], v[210:213], v[68:71]
	v_mfma_f32_16x16x32_bf16 v[64:67], v[178:181], v[210:213], v[64:67]
	s_barrier
	s_add_i32 s43, s34, s24
	v_lshl_add_u64 v[214:215], s[18:19], 0, v[142:143]
	s_mov_b32 m0, s43
	ds_read_b128 v[182:185], v169 offset:16384
	ds_read_b128 v[186:189], v169 offset:17408
	ds_read_b128 v[190:193], v169 offset:18432
	ds_read_b128 v[194:197], v169 offset:19456
	ds_read_b128 v[198:201], v169 offset:20480
	ds_read_b128 v[202:205], v169 offset:21504
	ds_read_b128 v[206:209], v169 offset:22528
	ds_read_b128 v[210:213], v169 offset:23552
	global_load_lds_dwordx4 v[214:215], off
	s_add_i32 m0, s43, 0x2000
	s_add_u32 s44, s18, 0xb0000
	v_lshl_add_u64 v[216:217], s[18:19], 0, v[146:147]
	s_addc_u32 s45, s19, 0
	s_add_i32 s43, s35, s24
	global_load_lds_dwordx4 v[216:217], off
	v_lshl_add_u64 v[218:219], s[44:45], 0, v[142:143]
	s_mov_b32 m0, s43
	v_lshl_add_u64 v[220:221], s[20:21], 0, v[144:145]
	global_load_lds_dwordx4 v[218:219], off
	v_lshl_add_u64 v[218:219], s[44:45], 0, v[146:147]
	s_add_i32 m0, s43, 0x2000
	s_nop 0
	global_load_lds_dwordx4 v[218:219], off
	v_lshl_add_u64 v[218:219], s[20:21], 0, v[140:141]
	s_mov_b32 m0, s25
	s_nop 0
	global_load_lds_dwordx4 v[218:219], off
	s_mov_b32 m0, s26
	s_nop 0
	global_load_lds_dwordx4 v[220:221], off
	s_waitcnt vmcnt(8)
	s_waitcnt lgkmcnt(0)
	s_barrier
; #define PG8_STAGE(bufoff, gbase, voff) do { _Pragma("unroll") for (int _i = 0; _i < 2; ++_i) \
;         __builtin_amdgcn_global_load_lds((const unsigned*)((const char*)(gbase) + (voff)[_i]), (PG8_LAS unsigned*)(lds + (bufoff) + ldsw + _i * 8192), 16, 0, 0); } while (0)
; #define PG8_LDA(dst, b, h) do { _Pragma("unroll") for (int m = 0; m < 4; ++m) _Pragma("unroll") for (int k = 0; k < 2; ++k) dst[m][k] = *(const PG8_LAS bf16x8*)(lds + PG8_SA(b, h) + aoff + m * 2048 + k * 1024); } while (0)
; #define PG8_LDB(dst, b, h) do { _Pragma("unroll") for (int n = 0; n < 2; ++n) _Pragma("unroll") for (int k = 0; k < 2; ++k) dst[n][k] = *(const PG8_LAS bf16x8*)(lds + PG8_SB(b, h) + boff + n * 2048 + k * 1024); } while (0)
; #define PG8_MMA(ai, bj, At, Bt) do { __builtin_amdgcn_s_setprio(1); _Pragma("unroll") for (int m = 0; m < 4; ++m) _Pragma("unroll") for (int n = 0; n < 2; ++n) _Pragma("unroll") for (int k = 0; k < 2; ++k) \
;         acc[ai][bj][m][n] = mma16<F16>(Bt[n][k], At[m][k], acc[ai][bj][m][n]); __builtin_amdgcn_s_setprio(0); } while (0)
; #define PG8_WAIT_V(n) asm volatile("s_waitcnt vmcnt(" #n ")" ::: "memory")
; #define PG8_WAIT_L(n) asm volatile("s_waitcnt lgkmcnt(" #n ")" ::: "memory")
; #define PG8_BAR __builtin_amdgcn_s_barrier()
; #define PG8_SCHED __builtin_amdgcn_sched_barrier(0)
; template <class Epi, class Sched, bool ALIGN_EPI = false, bool SP2 = false, bool F16 = false>
; __device__ __forceinline__ void gemm_phase(PG8_LAS unsigned char* lds, const Gemm g, const Sched& S, const Epi& E) {
;     ...
;             PG8_WAIT_V(8); PG8_WAIT_L(0); PG8_BAR; PG8_MMA(1, 0, At, B0); PG8_MMA(1, 1, At, B1); PG8_BAR; PG8_SCHED;
;             PG8_LDB(B0, 1, 0); PG8_LDB(B1, 1, 1); PG8_SCHED; PG8_LDA(At, 1, 0); PG8_STAGE(PG8_SA(0, 1), a2 + hstep, voffA);
;             PG8_WAIT_V(8); PG8_WAIT_L(0); PG8_BAR; PG8_MMA(0, 0, At, B0); PG8_MMA(0, 1, At, B1); PG8_BAR; PG8_SCHED;
	s_waitcnt lgkmcnt(0)
	v_mfma_f32_16x16x32_bf16 v[60:63], v[128:131], v[182:185], v[60:63]
	v_mfma_f32_16x16x32_bf16 v[56:59], v[136:139], v[182:185], v[56:59]
	v_mfma_f32_16x16x32_bf16 v[48:51], v[128:131], v[190:193], v[48:51]
	v_mfma_f32_16x16x32_bf16 v[40:43], v[136:139], v[190:193], v[40:43]
	v_mfma_f32_16x16x32_bf16 v[32:35], v[128:131], v[198:201], v[32:35]
	v_mfma_f32_16x16x32_bf16 v[24:27], v[136:139], v[198:201], v[24:27]
	v_mfma_f32_16x16x32_bf16 v[16:19], v[128:131], v[206:209], v[16:19]
	v_mfma_f32_16x16x32_bf16 v[8:11], v[136:139], v[206:209], v[8:11]
	v_mfma_f32_16x16x32_bf16 v[60:63], v[132:135], v[186:189], v[60:63]
	v_mfma_f32_16x16x32_bf16 v[56:59], v[156:159], v[186:189], v[56:59]
	v_mfma_f32_16x16x32_bf16 v[48:51], v[132:135], v[194:197], v[48:51]
	v_mfma_f32_16x16x32_bf16 v[40:43], v[156:159], v[194:197], v[40:43]
	v_mfma_f32_16x16x32_bf16 v[32:35], v[132:135], v[202:205], v[32:35]
	v_mfma_f32_16x16x32_bf16 v[24:27], v[156:159], v[202:205], v[24:27]
	v_mfma_f32_16x16x32_bf16 v[16:19], v[132:135], v[210:213], v[16:19]
	v_mfma_f32_16x16x32_bf16 v[8:11], v[156:159], v[210:213], v[8:11]
	v_mfma_f32_16x16x32_bf16 v[52:55], v[160:163], v[182:185], v[52:55]
	v_mfma_f32_16x16x32_bf16 v[44:47], v[174:177], v[182:185], v[44:47]
	v_mfma_f32_16x16x32_bf16 v[36:39], v[160:163], v[190:193], v[36:39]
	v_mfma_f32_16x16x32_bf16 v[28:31], v[174:177], v[190:193], v[28:31]
	v_mfma_f32_16x16x32_bf16 v[20:23], v[160:163], v[198:201], v[20:23]
	v_mfma_f32_16x16x32_bf16 v[12:15], v[174:177], v[198:201], v[12:15]
	v_mfma_f32_16x16x32_bf16 v[4:7], v[160:163], v[206:209], v[4:7]
	v_mfma_f32_16x16x32_bf16 v[0:3], v[174:177], v[206:209], v[0:3]
	v_mfma_f32_16x16x32_bf16 v[52:55], v[170:173], v[186:189], v[52:55]
	v_mfma_f32_16x16x32_bf16 v[44:47], v[178:181], v[186:189], v[44:47]
	v_mfma_f32_16x16x32_bf16 v[36:39], v[170:173], v[194:197], v[36:39]
	v_mfma_f32_16x16x32_bf16 v[28:31], v[178:181], v[194:197], v[28:31]
	v_mfma_f32_16x16x32_bf16 v[20:23], v[170:173], v[202:205], v[20:23]
	v_mfma_f32_16x16x32_bf16 v[12:15], v[178:181], v[202:205], v[12:15]
	v_mfma_f32_16x16x32_bf16 v[4:7], v[170:173], v[210:213], v[4:7]
	v_mfma_f32_16x16x32_bf16 v[0:3], v[178:181], v[210:213], v[0:3]
	s_barrier
	s_add_i32 s43, 0, 0x18000
	s_add_i32 s44, 0, 0x1c000
	v_add_u32_e32 v156, s43, v165
	v_add_u32_e32 v178, s44, v165
	ds_read_b128 v[128:131], v156
	ds_read_b128 v[132:135], v156 offset:1024
	ds_read_b128 v[136:139], v156 offset:2048
	ds_read_b128 v[156:159], v156 offset:3072
	ds_read_b128 v[160:163], v178
	ds_read_b128 v[170:173], v178 offset:1024
	ds_read_b128 v[174:177], v178 offset:2048
	ds_read_b128 v[178:181], v178 offset:3072
	s_add_u32 s20, s20, 0xb0000
	s_addc_u32 s21, s21, 0
	s_mov_b32 m0, s27
	v_lshl_add_u64 v[222:223], s[20:21], 0, v[140:141]
	ds_read_b128 v[182:185], v169 offset:32768
	ds_read_b128 v[186:189], v169 offset:33792
	ds_read_b128 v[190:193], v169 offset:34816
	ds_read_b128 v[194:197], v169 offset:35840
	ds_read_b128 v[198:201], v169 offset:36864
	ds_read_b128 v[202:205], v169 offset:37888
	ds_read_b128 v[206:209], v169 offset:38912
	ds_read_b128 v[210:213], v169 offset:39936
	global_load_lds_dwordx4 v[222:223], off
	v_lshl_add_u64 v[222:223], s[20:21], 0, v[144:145]
	s_mov_b32 m0, s28
	s_nop 0
	global_load_lds_dwordx4 v[222:223], off
	s_waitcnt vmcnt(8)
	s_waitcnt lgkmcnt(0)
	s_barrier
	s_waitcnt lgkmcnt(0)
	v_mfma_f32_16x16x32_bf16 v[124:127], v[128:131], v[182:185], v[124:127]
	v_mfma_f32_16x16x32_bf16 v[120:123], v[136:139], v[182:185], v[120:123]
	v_mfma_f32_16x16x32_bf16 v[116:119], v[128:131], v[190:193], v[116:119]
	v_mfma_f32_16x16x32_bf16 v[112:115], v[136:139], v[190:193], v[112:115]
	v_mfma_f32_16x16x32_bf16 v[100:103], v[128:131], v[198:201], v[100:103]
	v_mfma_f32_16x16x32_bf16 v[88:91], v[136:139], v[198:201], v[88:91]
	v_mfma_f32_16x16x32_bf16 v[80:83], v[128:131], v[206:209], v[80:83]
	v_mfma_f32_16x16x32_bf16 v[72:75], v[136:139], v[206:209], v[72:75]
	v_mfma_f32_16x16x32_bf16 v[124:127], v[132:135], v[186:189], v[124:127]
	v_mfma_f32_16x16x32_bf16 v[120:123], v[156:159], v[186:189], v[120:123]
	v_mfma_f32_16x16x32_bf16 v[116:119], v[132:135], v[194:197], v[116:119]
	v_mfma_f32_16x16x32_bf16 v[112:115], v[156:159], v[194:197], v[112:115]
	v_mfma_f32_16x16x32_bf16 v[100:103], v[132:135], v[202:205], v[100:103]
	v_mfma_f32_16x16x32_bf16 v[88:91], v[156:159], v[202:205], v[88:91]
	v_mfma_f32_16x16x32_bf16 v[80:83], v[132:135], v[210:213], v[80:83]
	v_mfma_f32_16x16x32_bf16 v[72:75], v[156:159], v[210:213], v[72:75]
	v_mfma_f32_16x16x32_bf16 v[108:111], v[160:163], v[182:185], v[108:111]
	v_mfma_f32_16x16x32_bf16 v[104:107], v[174:177], v[182:185], v[104:107]
	v_mfma_f32_16x16x32_bf16 v[96:99], v[160:163], v[190:193], v[96:99]
	v_mfma_f32_16x16x32_bf16 v[92:95], v[174:177], v[190:193], v[92:95]
	v_mfma_f32_16x16x32_bf16 v[84:87], v[160:163], v[198:201], v[84:87]
	v_mfma_f32_16x16x32_bf16 v[76:79], v[174:177], v[198:201], v[76:79]
	v_mfma_f32_16x16x32_bf16 v[68:71], v[160:163], v[206:209], v[68:71]
	v_mfma_f32_16x16x32_bf16 v[64:67], v[174:177], v[206:209], v[64:67]
	v_mfma_f32_16x16x32_bf16 v[108:111], v[170:173], v[186:189], v[108:111]
	v_mfma_f32_16x16x32_bf16 v[104:107], v[178:181], v[186:189], v[104:107]
	v_mfma_f32_16x16x32_bf16 v[96:99], v[170:173], v[194:197], v[96:99]
	v_mfma_f32_16x16x32_bf16 v[92:95], v[178:181], v[194:197], v[92:95]
	v_mfma_f32_16x16x32_bf16 v[84:87], v[170:173], v[202:205], v[84:87]
	v_mfma_f32_16x16x32_bf16 v[76:79], v[178:181], v[202:205], v[76:79]
	v_mfma_f32_16x16x32_bf16 v[68:71], v[170:173], v[210:213], v[68:71]
	v_mfma_f32_16x16x32_bf16 v[64:67], v[178:181], v[210:213], v[64:67]
	s_barrier
; #define PG8_STAGE(bufoff, gbase, voff) do { _Pragma("unroll") for (int _i = 0; _i < 2; ++_i) \
;         __builtin_amdgcn_global_load_lds((const unsigned*)((const char*)(gbase) + (voff)[_i]), (PG8_LAS unsigned*)(lds + (bufoff) + ldsw + _i * 8192), 16, 0, 0); } while (0)
; #define PG8_LDA(dst, b, h) do { _Pragma("unroll") for (int m = 0; m < 4; ++m) _Pragma("unroll") for (int k = 0; k < 2; ++k) dst[m][k] = *(const PG8_LAS bf16x8*)(lds + PG8_SA(b, h) + aoff + m * 2048 + k * 1024); } while (0)
; #define PG8_MMA(ai, bj, At, Bt) do { __builtin_amdgcn_s_setprio(1); _Pragma("unroll") for (int m = 0; m < 4; ++m) _Pragma("unroll") for (int n = 0; n < 2; ++n) _Pragma("unroll") for (int k = 0; k < 2; ++k) \
;         acc[ai][bj][m][n] = mma16<F16>(Bt[n][k], At[m][k], acc[ai][bj][m][n]); __builtin_amdgcn_s_setprio(0); } while (0)
; #define PG8_WAIT_V(n) asm volatile("s_waitcnt vmcnt(" #n ")" ::: "memory")
; #define PG8_WAIT_L(n) asm volatile("s_waitcnt lgkmcnt(" #n ")" ::: "memory")
; #define PG8_BAR __builtin_amdgcn_s_barrier()
; #define PG8_SCHED __builtin_amdgcn_sched_barrier(0)
; template <class Epi, class Sched, bool ALIGN_EPI = false, bool SP2 = false, bool F16 = false>
; __device__ __forceinline__ void gemm_phase(PG8_LAS unsigned char* lds, const Gemm g, const Sched& S, const Epi& E) {
;     ...
;         for (int t = 0; t < nt; t += 2) {
;             const bool last = (t == nt - 2);
;     ...
;             PG8_LDA(At, 1, 1); PG8_STAGE(PG8_SB(1, 0), b3, voffB); PG8_STAGE(PG8_SB(1, 1), b3 + hstep, voffB); PG8_STAGE(PG8_SA(1, 0), a3, voffA);
;             PG8_WAIT_V(8); PG8_WAIT_L(0); PG8_BAR; PG8_MMA(1, 0, At, B0); PG8_MMA(1, 1, At, B1); PG8_BAR; PG8_SCHED;
;     ...
;         if constexpr (ALIGN_EPI) { if (wr == 0) PG8_BAR; }
	s_add_i32 s20, s43, s24
	v_lshl_add_u64 v[214:215], v[214:215], 0, s[10:11]
	s_mov_b32 m0, s20
	ds_read_b128 v[182:185], v169 offset:49152
	ds_read_b128 v[186:189], v169 offset:50176
	ds_read_b128 v[190:193], v169 offset:51200
	ds_read_b128 v[194:197], v169 offset:52224
	ds_read_b128 v[198:201], v169 offset:53248
	ds_read_b128 v[202:205], v169 offset:54272
	ds_read_b128 v[206:209], v169 offset:55296
	ds_read_b128 v[210:213], v169 offset:56320
	global_load_lds_dwordx4 v[214:215], off
	s_add_i32 m0, s20, 0x2000
	s_add_u32 s18, s18, 0xb0080
	v_lshl_add_u64 v[214:215], v[216:217], 0, s[10:11]
	s_addc_u32 s19, s19, 0
	s_add_i32 s20, s44, s24
	global_load_lds_dwordx4 v[214:215], off
	v_lshl_add_u64 v[214:215], s[18:19], 0, v[142:143]
	s_mov_b32 m0, s20
	s_nop 0
	global_load_lds_dwordx4 v[214:215], off
	v_lshl_add_u64 v[214:215], s[18:19], 0, v[146:147]
	s_add_i32 m0, s20, 0x2000
	s_nop 0
	global_load_lds_dwordx4 v[214:215], off
	v_lshl_add_u64 v[214:215], v[218:219], 0, s[10:11]
	s_mov_b32 m0, s30
	s_nop 0
	global_load_lds_dwordx4 v[214:215], off
	v_lshl_add_u64 v[214:215], v[220:221], 0, s[10:11]
	s_mov_b32 m0, s31
	s_nop 0
	global_load_lds_dwordx4 v[214:215], off
	s_waitcnt vmcnt(8)
	s_waitcnt lgkmcnt(0)
	s_barrier
	s_waitcnt lgkmcnt(0)
	v_mfma_f32_16x16x32_bf16 v[60:63], v[128:131], v[182:185], v[60:63]
	v_mfma_f32_16x16x32_bf16 v[56:59], v[136:139], v[182:185], v[56:59]
	v_mfma_f32_16x16x32_bf16 v[48:51], v[128:131], v[190:193], v[48:51]
	v_mfma_f32_16x16x32_bf16 v[40:43], v[136:139], v[190:193], v[40:43]
	v_mfma_f32_16x16x32_bf16 v[32:35], v[128:131], v[198:201], v[32:35]
	v_mfma_f32_16x16x32_bf16 v[24:27], v[136:139], v[198:201], v[24:27]
	v_mfma_f32_16x16x32_bf16 v[16:19], v[128:131], v[206:209], v[16:19]
	v_mfma_f32_16x16x32_bf16 v[8:11], v[136:139], v[206:209], v[8:11]
	v_mfma_f32_16x16x32_bf16 v[60:63], v[132:135], v[186:189], v[60:63]
	v_mfma_f32_16x16x32_bf16 v[56:59], v[156:159], v[186:189], v[56:59]
	v_mfma_f32_16x16x32_bf16 v[48:51], v[132:135], v[194:197], v[48:51]
	v_mfma_f32_16x16x32_bf16 v[40:43], v[156:159], v[194:197], v[40:43]
	v_mfma_f32_16x16x32_bf16 v[32:35], v[132:135], v[202:205], v[32:35]
	v_mfma_f32_16x16x32_bf16 v[24:27], v[156:159], v[202:205], v[24:27]
	v_mfma_f32_16x16x32_bf16 v[16:19], v[132:135], v[210:213], v[16:19]
	v_mfma_f32_16x16x32_bf16 v[8:11], v[156:159], v[210:213], v[8:11]
	v_mfma_f32_16x16x32_bf16 v[52:55], v[160:163], v[182:185], v[52:55]
	v_mfma_f32_16x16x32_bf16 v[44:47], v[174:177], v[182:185], v[44:47]
	v_mfma_f32_16x16x32_bf16 v[36:39], v[160:163], v[190:193], v[36:39]
	v_mfma_f32_16x16x32_bf16 v[28:31], v[174:177], v[190:193], v[28:31]
	v_mfma_f32_16x16x32_bf16 v[20:23], v[160:163], v[198:201], v[20:23]
	v_mfma_f32_16x16x32_bf16 v[12:15], v[174:177], v[198:201], v[12:15]
	v_mfma_f32_16x16x32_bf16 v[4:7], v[160:163], v[206:209], v[4:7]
	v_mfma_f32_16x16x32_bf16 v[0:3], v[174:177], v[206:209], v[0:3]
	v_mfma_f32_16x16x32_bf16 v[52:55], v[170:173], v[186:189], v[52:55]
	v_mfma_f32_16x16x32_bf16 v[44:47], v[178:181], v[186:189], v[44:47]
	v_mfma_f32_16x16x32_bf16 v[36:39], v[170:173], v[194:197], v[36:39]
	v_mfma_f32_16x16x32_bf16 v[28:31], v[178:181], v[194:197], v[28:31]
	v_mfma_f32_16x16x32_bf16 v[20:23], v[170:173], v[202:205], v[20:23]
	v_mfma_f32_16x16x32_bf16 v[12:15], v[178:181], v[202:205], v[12:15]
	v_mfma_f32_16x16x32_bf16 v[4:7], v[170:173], v[210:213], v[4:7]
	v_mfma_f32_16x16x32_bf16 v[0:3], v[178:181], v[210:213], v[0:3]
	s_barrier
	s_add_i32 s42, s42, 2
	s_add_u32 s16, s16, 0x100
	s_addc_u32 s17, s17, 0
	s_add_u32 s40, s40, 0x100
	s_addc_u32 s41, s41, 0
	s_cmp_gt_u32 s42, 41
	s_cbranch_scc0 .LBB0_746
	s_and_b64 vcc, exec, s[12:13]
	s_cbranch_vccz .LBB0_749
	s_barrier
